# pipelined GEMM K-loops: the first two LDS-DMA pieces of the following stage are issued right after the stage barrier (as soon as the buffer is free), the rest two per MFMA group
# speedup vs baseline: 1.0041x; 1.0041x over previous
; template <int EPI, int MI>
; DI void gemm_tile(const GemmDesc& g, int tm, int tn, char* smem) {
;     ...
;   const int tid = get_tid(), lane = tid & 63, wave = tid >> 6, r = lane & 31, hh = lane >> 5;
;   const int wm = wave >> 1, wn = wave & 1;
;   const int m0 = tm * BM, n0 = tn * 128;
;   const int nk = g.K >> 6;
;   f32x16 acc[MI][2];
; #pragma unroll
;   for (int a = 0; a < MI; ++a)
; #pragma unroll
;     for (int b = 0; b < 2; ++b)
; #pragma unroll
;       for (int i = 0; i < 16; ++i) acc[a][b][i] = 0.f;
;   const int srow = tid >> 3;
;   const int schunk = (tid & 7) ^ ((srow & 7) ^ ((srow >> 3) & 3));
;     ...
;   const int rowA = wm * (32 * MI) + r, rowB = wn * 64 + r;
;   const int hk = hh ^ ((r & 7) ^ ((r >> 3) & 3));
;     ...
;   G_GLDS(0, 0);
;   asm volatile("s_waitcnt vmcnt(0)" ::: "memory");
;   __syncthreads();
; template <int EPI, int MI>
; DI void gemm_phase(const GemmDesc& g, char* smem, int vb, int nvb) {
;     ...
;   const int mPer = xm ? (g.nM >> 3) : g.nM;
;   const int PM = (mPer % 9 == 0) ? 9 : ((mPer & 7) == 0 ? 8 : ((mPer % 6) == 0 ? 6 : mPer));
;   const int per = PM * g.nN;
;   const int local = mPer * g.nN;
;   const int start = xm ? (vb >> 3) : vb, step = xm ? (nvb >> 3) : nvb;
;   const int mbase = xm ? xcd * mPer : 0;
;   for (int q = start; q < local; q += step) {
;     const int mg = q / per;
;     const int rem = q - mg * per;
;     const int tn = rem / PM;
;     const int tm = mbase + mg * PM + (rem - tn * PM);
.LBB0_202:
	s_abs_i32 s1, s5
	v_readlane_b32 s15, v219, 45
	s_mul_hi_u32 s15, s1, s15
	v_readlane_b32 s18, v219, 44
	s_mul_i32 s16, s15, s18
	s_sub_i32 s1, s1, s16
	s_ashr_i32 s0, s5, 31
	s_add_i32 s16, s15, 1
	s_sub_i32 s17, s1, s18
	s_cmp_ge_u32 s1, s18
	s_cselect_b32 s15, s16, s15
	s_cselect_b32 s1, s17, s1
	s_add_i32 s16, s15, 1
	s_cmp_ge_u32 s1, s18
	s_cselect_b32 s1, s16, s15
	s_xor_b32 s1, s1, s0
	s_sub_i32 s15, s1, s0
	s_mul_i32 s16, s15, s18
	s_sub_i32 s16, s5, s16
	s_abs_i32 s18, s16
	v_readlane_b32 s19, v219, 46
	s_mul_hi_u32 s19, s18, s19
	v_readlane_b32 s42, v218, 32
	s_mul_i32 s38, s19, s42
	s_sub_i32 s18, s18, s38
	s_ashr_i32 s17, s16, 31
	s_add_i32 s38, s19, 1
	s_sub_i32 s39, s18, s42
	s_cmp_ge_u32 s18, s42
	s_cselect_b32 s19, s38, s19
	s_cselect_b32 s18, s39, s18
	s_add_i32 s38, s19, 1
	s_cmp_ge_u32 s18, s42
	s_cselect_b32 s18, s38, s19
	s_xor_b32 s18, s18, s17
	s_sub_i32 s39, s18, s17
	s_sub_i32 s15, s15, s39
	v_mov_b32_e32 v4, v132
	s_mul_i32 s15, s15, s42
	s_add_i32 s16, s16, s54
	s_add_i32 s38, s16, s15
	v_ashrrev_i32_e32 v97, 3, v4
	v_ashrrev_i32_e32 v120, 7, v4
	v_bfe_u32 v0, v4, 6, 2
	v_xor_b32_e32 v1, v97, v4
	s_mulk_i32 s38, 0xc0
	v_and_b32_e32 v121, 31, v4
	v_bitop3_b32 v2, v1, v0, 7 bitop3:0x6c
	v_mul_lo_u32 v0, v120, s6
	v_and_b32_e32 v115, 7, v4
	v_or_b32_e32 v5, v0, v121
	v_lshrrev_b32_e32 v0, 3, v4
	s_waitcnt vmcnt(10)
	v_add_u32_e32 v98, s38, v97
	v_bfe_u32 v122, v4, 5, 1
	v_bitop3_b32 v0, v0, v115, 3 bitop3:0x6c
	v_ashrrev_i32_e32 v99, 31, v98
	v_xor_b32_e32 v6, v0, v122
	v_lshlrev_b64 v[0:1], 11, v[98:99]
	v_readlane_b32 s42, v223, 59
	v_lshlrev_b32_e32 v99, 4, v4
	v_readlane_b32 s43, v223, 60
	v_lshlrev_b32_e32 v100, 4, v2
	v_lshl_add_u32 v2, s39, 7, v97
	v_add_u32_e32 v124, 0, v99
	v_lshl_add_u64 v[0:1], s[42:43], 0, v[0:1]
	v_mov_b32_e32 v101, v96
	v_ashrrev_i32_e32 v3, 31, v2
	v_readfirstlane_b32 s15, v124
	v_add_u32_e32 v125, 0x1000, v124
	v_lshl_add_u64 v[0:1], v[0:1], 0, v[100:101]
	v_lshlrev_b64 v[2:3], 11, v[2:3]
	s_mov_b32 m0, s15
	s_mov_b64 s[42:43], 0x10000
	v_readfirstlane_b32 s15, v125
	v_add_u32_e32 v126, 0x2000, v124
	s_waitcnt vmcnt(9)
	v_lshl_add_u64 v[102:103], s[70:71], 0, v[2:3]
	global_load_lds_dwordx4 v[0:1], off
	v_lshl_add_u64 v[2:3], v[0:1], 0, s[42:43]
	s_mov_b32 m0, s15
	s_mov_b64 s[44:45], 0x20000
	v_readfirstlane_b32 s15, v126
	v_add_u32_e32 v127, 0x3000, v124
	global_load_lds_dwordx4 v[2:3], off
	v_lshl_add_u64 v[2:3], v[0:1], 0, s[44:45]
	s_mov_b32 m0, s15
	s_mov_b64 s[46:47], 0x30000
	v_readfirstlane_b32 s15, v127
	v_add_u32_e32 v128, 0x4000, v124
	global_load_lds_dwordx4 v[2:3], off
	v_lshl_add_u64 v[2:3], v[0:1], 0, s[46:47]
	s_mov_b32 m0, s15
	s_mov_b64 s[52:53], 0x40000
	v_readfirstlane_b32 s15, v128
	v_add_u32_e32 v129, 0x5000, v124
	global_load_lds_dwordx4 v[2:3], off
	v_lshl_add_u64 v[2:3], v[0:1], 0, s[52:53]
	s_mov_b32 m0, s15
	s_mov_b64 s[52:53], 0x50000
	v_readfirstlane_b32 s15, v129
	v_add_u32_e32 v130, 0xc000, v124
	global_load_lds_dwordx4 v[2:3], off
	v_lshl_add_u64 v[0:1], v[0:1], 0, s[52:53]
	s_mov_b32 m0, s15
	v_readfirstlane_b32 s15, v130
	v_add_u32_e32 v131, 0xd000, v124
	global_load_lds_dwordx4 v[0:1], off
	v_lshl_add_u64 v[0:1], v[102:103], 0, v[100:101]
	s_mov_b32 m0, s15
	v_readfirstlane_b32 s15, v131
	v_add_u32_e32 v153, 0xe000, v124
	global_load_lds_dwordx4 v[0:1], off
	v_lshl_add_u64 v[2:3], v[0:1], 0, s[42:43]
	s_mov_b32 m0, s15
	v_readfirstlane_b32 s15, v153
	v_add_u32_e32 v154, 0xf000, v124
	global_load_lds_dwordx4 v[2:3], off
	v_lshl_add_u64 v[2:3], v[0:1], 0, s[44:45]
	s_mov_b32 m0, s15
	v_readfirstlane_b32 s15, v154
	global_load_lds_dwordx4 v[2:3], off
	v_lshl_add_u64 v[0:1], v[0:1], 0, s[46:47]
	s_mov_b32 m0, s15
	s_mul_i32 s0, s0, 43
	global_load_lds_dwordx4 v[0:1], off
	s_add_i32 s17, s17, s0
	s_sub_i32 s0, s17, s18
	s_mul_i32 s1, s1, 43
	s_sub_i32 s0, s0, s1
	v_readlane_b32 s1, v218, 33
	v_bfe_u32 v123, v4, 6, 1
	v_lshlrev_b32_e32 v0, 7, v121
	s_mul_i32 s0, s1, s0
	v_lshl_or_b32 v0, v123, 13, v0
	s_add_i32 s0, s0, s4
	v_add_u32_e32 v156, 0, v0
	v_add_u32_e32 v158, s10, v0
	v_add_u32_e32 v0, s0, v97
	v_ashrrev_i32_e32 v1, 31, v0
	s_waitcnt vmcnt(0)
	v_lshlrev_b64 v[0:1], 11, v[0:1]
	v_lshlrev_b32_e32 v157, 4, v6
	v_lshl_add_u64 v[104:105], s[70:71], 0, v[0:1]
	v_mov_b32_e32 v0, 0
	v_lshl_add_u32 v155, v5, 7, 0
	s_mov_b32 s15, 0
	v_mov_b32_e32 v1, v0
	v_mov_b32_e32 v2, v0
	v_mov_b32_e32 v3, v0
	v_mov_b32_e32 v4, v0
	v_mov_b32_e32 v5, v0
	v_mov_b32_e32 v6, v0
	v_mov_b32_e32 v7, v0
	v_mov_b32_e32 v8, v0
	v_mov_b32_e32 v9, v0
	v_mov_b32_e32 v10, v0
	v_mov_b32_e32 v11, v0
	v_mov_b32_e32 v12, v0
	v_mov_b32_e32 v13, v0
	v_mov_b32_e32 v14, v0
	v_mov_b32_e32 v15, v0
	v_mov_b32_e32 v16, v0
	v_mov_b32_e32 v17, v0
	v_mov_b32_e32 v18, v0
	v_mov_b32_e32 v19, v0
	v_mov_b32_e32 v20, v0
	v_mov_b32_e32 v21, v0
	v_mov_b32_e32 v22, v0
	v_mov_b32_e32 v23, v0
	v_mov_b32_e32 v24, v0
	v_mov_b32_e32 v25, v0
	v_mov_b32_e32 v26, v0
	v_mov_b32_e32 v27, v0
	v_mov_b32_e32 v28, v0
	v_mov_b32_e32 v29, v0
	v_mov_b32_e32 v30, v0
	v_mov_b32_e32 v31, v0
	v_mov_b32_e32 v32, v0
	v_mov_b32_e32 v33, v0
	v_mov_b32_e32 v34, v0
	v_mov_b32_e32 v35, v0
	v_mov_b32_e32 v36, v0
	v_mov_b32_e32 v37, v0
	v_mov_b32_e32 v38, v0
	v_mov_b32_e32 v39, v0
	v_mov_b32_e32 v40, v0
	v_mov_b32_e32 v41, v0
	v_mov_b32_e32 v42, v0
	v_mov_b32_e32 v43, v0
	v_mov_b32_e32 v44, v0
	v_mov_b32_e32 v45, v0
	v_mov_b32_e32 v46, v0
	v_mov_b32_e32 v47, v0
	v_mov_b32_e32 v48, v0
	s_waitcnt vmcnt(0)
; template <int EPI, int MI>
; DI void gemm_tile(const GemmDesc& g, int tm, int tn, char* smem) {
;     ...
;   f32x16 acc[MI][2];
; #pragma unroll
;   for (int a = 0; a < MI; ++a)
; #pragma unroll
;     for (int b = 0; b < 2; ++b)
; #pragma unroll
;       for (int i = 0; i < 16; ++i) acc[a][b][i] = 0.f;
;   const int srow = tid >> 3;
;   const int schunk = (tid & 7) ^ ((srow & 7) ^ ((srow >> 3) & 3));
;     ...
;   const int rowA = wm * (32 * MI) + r, rowB = wn * 64 + r;
;   const int hk = hh ^ ((r & 7) ^ ((r >> 3) & 3));
;     ...
;   G_GLDS(0, 0);
;   asm volatile("s_waitcnt vmcnt(0)" ::: "memory");
;   __syncthreads();
;   for (int kt = 0; kt < nk; kt += 2) {
;     if (kt + 1 < nk) G_GLDS(kt + 1, 1);
;     G_COMPUTE(0);
;     asm volatile("s_waitcnt vmcnt(0)" ::: "memory");
;     __syncthreads();
;     if (kt + 1 < nk) {
;       if (kt + 2 < nk) G_GLDS(kt + 2, 0);
;       G_COMPUTE(1);
;       asm volatile("s_waitcnt vmcnt(0)" ::: "memory");
;       __syncthreads();
;     }
;   }
	v_mov_b32_e32 v49, v0
	v_mov_b32_e32 v50, v0
	v_mov_b32_e32 v51, v0
	v_mov_b32_e32 v52, v0
	v_mov_b32_e32 v53, v0
	v_mov_b32_e32 v54, v0
	v_mov_b32_e32 v55, v0
	v_mov_b32_e32 v56, v0
	v_mov_b32_e32 v57, v0
	v_mov_b32_e32 v58, v0
	v_mov_b32_e32 v59, v0
	v_mov_b32_e32 v60, v0
	v_mov_b32_e32 v61, v0
	v_mov_b32_e32 v62, v0
	v_mov_b32_e32 v63, v0
	v_mov_b32_e32 v64, v0
	v_mov_b32_e32 v65, v0
	v_mov_b32_e32 v66, v0
	v_mov_b32_e32 v67, v0
	v_mov_b32_e32 v68, v0
	v_mov_b32_e32 v69, v0
	v_mov_b32_e32 v70, v0
	v_mov_b32_e32 v71, v0
	v_mov_b32_e32 v72, v0
	v_mov_b32_e32 v73, v0
	v_mov_b32_e32 v74, v0
	v_mov_b32_e32 v75, v0
	v_mov_b32_e32 v76, v0
	v_mov_b32_e32 v77, v0
	v_mov_b32_e32 v78, v0
	v_mov_b32_e32 v79, v0
	v_mov_b32_e32 v80, v0
	v_mov_b32_e32 v81, v0
	v_mov_b32_e32 v82, v0
	v_mov_b32_e32 v83, v0
	v_mov_b32_e32 v84, v0
	v_mov_b32_e32 v85, v0
	v_mov_b32_e32 v86, v0
	v_mov_b32_e32 v87, v0
	v_mov_b32_e32 v88, v0
	v_mov_b32_e32 v89, v0
	v_mov_b32_e32 v90, v0
	v_mov_b32_e32 v91, v0
	v_mov_b32_e32 v92, v0
	v_mov_b32_e32 v93, v0
	v_mov_b32_e32 v94, v0
	v_mov_b32_e32 v95, v0
	v_xor_b32_e32 v159, 32, v157
	v_xor_b32_e32 v160, 64, v157
	v_xor_b32_e32 v161, 0x60, v157
	s_mov_b64 s[18:19], 0x80
	s_mov_b64 s[42:43], 0x10080
	v_add_u32_e32 v162, v155, v157
	v_add_u32_e32 v163, v155, v159
	v_add_u32_e32 v164, v155, v160
	v_add_u32_e32 v165, v155, v161
	v_add_u32_e32 v166, v156, v157
	v_add_u32_e32 v167, v156, v159
	v_add_u32_e32 v168, v156, v160
	v_add_u32_e32 v169, v156, v161
	v_add_u32_e32 v170, v158, v157
	v_add_u32_e32 v171, v158, v159
	v_add_u32_e32 v172, v158, v160
	v_add_u32_e32 v173, v158, v161
	v_lshl_add_u64 v[174:175], v[104:105], 0, v[100:101]
	v_lshl_add_u64 v[176:177], v[102:103], 0, v[100:101]
	v_readfirstlane_b32 s100, v124
	s_waitcnt vmcnt(0) lgkmcnt(0)
	s_barrier
	s_add_u32 m0, s100, 0x6000
	v_lshl_add_u64 v[106:107], v[174:175], 0, s[96:97]
	global_load_lds_dwordx4 v[106:107], off
	s_add_u32 m0, s100, 0x7000
	v_lshl_add_u64 v[106:107], v[174:175], 0, s[50:51]
	global_load_lds_dwordx4 v[106:107], off
	ds_read_b128 v[236:239], v166 offset:49152
	ds_read_b128 v[240:243], v166 offset:53248
	ds_read_b128 v[224:227], v162
	ds_read_b128 v[228:231], v162 offset:4096
	s_mov_b32 s15, 0
.Lga_loop:
	ds_read_b128 v[232:235], v162 offset:8192
	s_waitcnt lgkmcnt(2)
	v_mfma_f32_32x32x16_bf16 v[80:95], v[224:227], v[236:239], v[80:95]
	v_mfma_f32_32x32x16_bf16 v[64:79], v[224:227], v[240:243], v[64:79]
	ds_read_b128 v[244:247], v167 offset:49152
	ds_read_b128 v[248:251], v167 offset:53248
	ds_read_b128 v[224:227], v163
	s_waitcnt lgkmcnt(4)
	v_mfma_f32_32x32x16_bf16 v[48:63], v[228:231], v[236:239], v[48:63]
	v_mfma_f32_32x32x16_bf16 v[32:47], v[228:231], v[240:243], v[32:47]
	s_add_u32 m0, s100, 0x8000
	v_lshl_add_u64 v[106:107], v[174:175], 0, s[24:25]
	global_load_lds_dwordx4 v[106:107], off
	s_add_u32 m0, s100, 0x9000
	v_lshl_add_u64 v[106:107], v[174:175], 0, s[26:27]
	global_load_lds_dwordx4 v[106:107], off
	ds_read_b128 v[228:231], v163 offset:4096
	s_waitcnt lgkmcnt(4)
	v_mfma_f32_32x32x16_bf16 v[16:31], v[232:235], v[236:239], v[16:31]
	v_mfma_f32_32x32x16_bf16 v[0:15], v[232:235], v[240:243], v[0:15]
	s_add_u32 m0, s100, 0xa000
	v_lshl_add_u64 v[106:107], v[174:175], 0, s[28:29]
	global_load_lds_dwordx4 v[106:107], off
	s_add_u32 m0, s100, 0xb000
	v_lshl_add_u64 v[106:107], v[174:175], 0, s[30:31]
	global_load_lds_dwordx4 v[106:107], off
	v_lshl_add_u64 v[174:175], v[174:175], 0, s[18:19]
	ds_read_b128 v[232:235], v163 offset:8192
	s_waitcnt lgkmcnt(2)
	v_mfma_f32_32x32x16_bf16 v[80:95], v[224:227], v[244:247], v[80:95]
	v_mfma_f32_32x32x16_bf16 v[64:79], v[224:227], v[248:251], v[64:79]
	s_add_u32 m0, s100, 0x10000
	v_lshl_add_u64 v[106:107], v[176:177], 0, s[18:19]
	global_load_lds_dwordx4 v[106:107], off
	s_add_u32 m0, s100, 0x11000
	v_lshl_add_u64 v[106:107], v[176:177], 0, s[42:43]
	global_load_lds_dwordx4 v[106:107], off
	ds_read_b128 v[236:239], v168 offset:49152
	ds_read_b128 v[240:243], v168 offset:53248
	ds_read_b128 v[224:227], v164
	s_waitcnt lgkmcnt(4)
	v_mfma_f32_32x32x16_bf16 v[48:63], v[228:231], v[244:247], v[48:63]
	v_mfma_f32_32x32x16_bf16 v[32:47], v[228:231], v[248:251], v[32:47]
	s_mov_b64 s[16:17], 0x20080
	s_add_u32 m0, s100, 0x12000
	v_lshl_add_u64 v[106:107], v[176:177], 0, s[16:17]
	global_load_lds_dwordx4 v[106:107], off
	s_mov_b64 s[16:17], 0x30080
	s_add_u32 m0, s100, 0x13000
	v_lshl_add_u64 v[106:107], v[176:177], 0, s[16:17]
	global_load_lds_dwordx4 v[106:107], off
	v_lshl_add_u64 v[176:177], v[176:177], 0, s[18:19]
	ds_read_b128 v[228:231], v164 offset:4096
	s_waitcnt lgkmcnt(4)
	v_mfma_f32_32x32x16_bf16 v[16:31], v[232:235], v[244:247], v[16:31]
	v_mfma_f32_32x32x16_bf16 v[0:15], v[232:235], v[248:251], v[0:15]
	ds_read_b128 v[232:235], v164 offset:8192
	s_waitcnt lgkmcnt(2)
	v_mfma_f32_32x32x16_bf16 v[80:95], v[224:227], v[236:239], v[80:95]
	v_mfma_f32_32x32x16_bf16 v[64:79], v[224:227], v[240:243], v[64:79]
	ds_read_b128 v[244:247], v169 offset:49152
	ds_read_b128 v[248:251], v169 offset:53248
	ds_read_b128 v[224:227], v165
	s_waitcnt lgkmcnt(4)
	v_mfma_f32_32x32x16_bf16 v[48:63], v[228:231], v[236:239], v[48:63]
	v_mfma_f32_32x32x16_bf16 v[32:47], v[228:231], v[240:243], v[32:47]
	ds_read_b128 v[228:231], v165 offset:4096
	s_waitcnt lgkmcnt(4)
	v_mfma_f32_32x32x16_bf16 v[16:31], v[232:235], v[236:239], v[16:31]
	v_mfma_f32_32x32x16_bf16 v[0:15], v[232:235], v[240:243], v[0:15]
	ds_read_b128 v[232:235], v165 offset:8192
	s_waitcnt lgkmcnt(2)
	v_mfma_f32_32x32x16_bf16 v[80:95], v[224:227], v[244:247], v[80:95]
	v_mfma_f32_32x32x16_bf16 v[64:79], v[224:227], v[248:251], v[64:79]
	s_waitcnt lgkmcnt(0)
	s_waitcnt vmcnt(0)
	s_barrier
	s_cmp_eq_u32 s15, 14
	s_cbranch_scc1 .Lga_noearly
	s_mov_b32 m0, s100
	v_lshl_add_u64 v[106:107], v[174:175], 0, s[96:97]
	global_load_lds_dwordx4 v[106:107], off
	s_add_u32 m0, s100, 0x1000
	v_lshl_add_u64 v[106:107], v[174:175], 0, s[50:51]
	global_load_lds_dwordx4 v[106:107], off
; template <int EPI, int MI>
; DI void gemm_tile(const GemmDesc& g, int tm, int tn, char* smem) {
;     ...
;   const int rowA = wm * (32 * MI) + r, rowB = wn * 64 + r;
;   const int hk = hh ^ ((r & 7) ^ ((r >> 3) & 3));
;     ...
;   G_GLDS(0, 0);
;   asm volatile("s_waitcnt vmcnt(0)" ::: "memory");
;   __syncthreads();
;   for (int kt = 0; kt < nk; kt += 2) {
;     if (kt + 1 < nk) G_GLDS(kt + 1, 1);
;     G_COMPUTE(0);
;     asm volatile("s_waitcnt vmcnt(0)" ::: "memory");
;     __syncthreads();
;     if (kt + 1 < nk) {
;       if (kt + 2 < nk) G_GLDS(kt + 2, 0);
;       G_COMPUTE(1);
;       asm volatile("s_waitcnt vmcnt(0)" ::: "memory");
;       __syncthreads();
;     }
;   }
.Lga_noearly:
	ds_read_b128 v[236:239], v170
	ds_read_b128 v[240:243], v170 offset:4096
	ds_read_b128 v[224:227], v162 offset:24576
	v_mfma_f32_32x32x16_bf16 v[48:63], v[228:231], v[244:247], v[48:63]
	v_mfma_f32_32x32x16_bf16 v[32:47], v[228:231], v[248:251], v[32:47]
	ds_read_b128 v[228:231], v162 offset:28672
	v_mfma_f32_32x32x16_bf16 v[16:31], v[232:235], v[244:247], v[16:31]
	v_mfma_f32_32x32x16_bf16 v[0:15], v[232:235], v[248:251], v[0:15]
	s_cmp_eq_u32 s15, 14
	s_cbranch_scc1 .Lga_last
	ds_read_b128 v[232:235], v162 offset:32768
	s_waitcnt lgkmcnt(2)
	v_mfma_f32_32x32x16_bf16 v[80:95], v[224:227], v[236:239], v[80:95]
	v_mfma_f32_32x32x16_bf16 v[64:79], v[224:227], v[240:243], v[64:79]
	ds_read_b128 v[244:247], v171
	ds_read_b128 v[248:251], v171 offset:4096
	ds_read_b128 v[224:227], v163 offset:24576
	s_waitcnt lgkmcnt(4)
	v_mfma_f32_32x32x16_bf16 v[48:63], v[228:231], v[236:239], v[48:63]
	v_mfma_f32_32x32x16_bf16 v[32:47], v[228:231], v[240:243], v[32:47]
	s_add_u32 m0, s100, 0x2000
	v_lshl_add_u64 v[106:107], v[174:175], 0, s[24:25]
	global_load_lds_dwordx4 v[106:107], off
	s_add_u32 m0, s100, 0x3000
	v_lshl_add_u64 v[106:107], v[174:175], 0, s[26:27]
	global_load_lds_dwordx4 v[106:107], off
	ds_read_b128 v[228:231], v163 offset:28672
	s_waitcnt lgkmcnt(4)
	v_mfma_f32_32x32x16_bf16 v[16:31], v[232:235], v[236:239], v[16:31]
	v_mfma_f32_32x32x16_bf16 v[0:15], v[232:235], v[240:243], v[0:15]
	s_add_u32 m0, s100, 0x4000
	v_lshl_add_u64 v[106:107], v[174:175], 0, s[28:29]
	global_load_lds_dwordx4 v[106:107], off
	s_add_u32 m0, s100, 0x5000
	v_lshl_add_u64 v[106:107], v[174:175], 0, s[30:31]
	global_load_lds_dwordx4 v[106:107], off
	v_lshl_add_u64 v[174:175], v[174:175], 0, s[18:19]
	ds_read_b128 v[232:235], v163 offset:32768
	s_waitcnt lgkmcnt(2)
	v_mfma_f32_32x32x16_bf16 v[80:95], v[224:227], v[244:247], v[80:95]
	v_mfma_f32_32x32x16_bf16 v[64:79], v[224:227], v[248:251], v[64:79]
	s_add_u32 m0, s100, 0xc000
	v_lshl_add_u64 v[106:107], v[176:177], 0, s[18:19]
	global_load_lds_dwordx4 v[106:107], off
	s_add_u32 m0, s100, 0xd000
	v_lshl_add_u64 v[106:107], v[176:177], 0, s[42:43]
	global_load_lds_dwordx4 v[106:107], off
	ds_read_b128 v[236:239], v172
	ds_read_b128 v[240:243], v172 offset:4096
	ds_read_b128 v[224:227], v164 offset:24576
	s_waitcnt lgkmcnt(4)
	v_mfma_f32_32x32x16_bf16 v[48:63], v[228:231], v[244:247], v[48:63]
	v_mfma_f32_32x32x16_bf16 v[32:47], v[228:231], v[248:251], v[32:47]
	s_mov_b64 s[16:17], 0x20080
	s_add_u32 m0, s100, 0xe000
	v_lshl_add_u64 v[106:107], v[176:177], 0, s[16:17]
	global_load_lds_dwordx4 v[106:107], off
	s_mov_b64 s[16:17], 0x30080
	s_add_u32 m0, s100, 0xf000
	v_lshl_add_u64 v[106:107], v[176:177], 0, s[16:17]
	global_load_lds_dwordx4 v[106:107], off
	v_lshl_add_u64 v[176:177], v[176:177], 0, s[18:19]
	ds_read_b128 v[228:231], v164 offset:28672
	s_waitcnt lgkmcnt(4)
	v_mfma_f32_32x32x16_bf16 v[16:31], v[232:235], v[244:247], v[16:31]
	v_mfma_f32_32x32x16_bf16 v[0:15], v[232:235], v[248:251], v[0:15]
	ds_read_b128 v[232:235], v164 offset:32768
	s_waitcnt lgkmcnt(2)
	v_mfma_f32_32x32x16_bf16 v[80:95], v[224:227], v[236:239], v[80:95]
	v_mfma_f32_32x32x16_bf16 v[64:79], v[224:227], v[240:243], v[64:79]
	ds_read_b128 v[244:247], v173
	ds_read_b128 v[248:251], v173 offset:4096
	ds_read_b128 v[224:227], v165 offset:24576
	s_waitcnt lgkmcnt(4)
	v_mfma_f32_32x32x16_bf16 v[48:63], v[228:231], v[236:239], v[48:63]
	v_mfma_f32_32x32x16_bf16 v[32:47], v[228:231], v[240:243], v[32:47]
	ds_read_b128 v[228:231], v165 offset:28672
	s_waitcnt lgkmcnt(4)
	v_mfma_f32_32x32x16_bf16 v[16:31], v[232:235], v[236:239], v[16:31]
	v_mfma_f32_32x32x16_bf16 v[0:15], v[232:235], v[240:243], v[0:15]
	ds_read_b128 v[232:235], v165 offset:32768
	s_waitcnt lgkmcnt(2)
	v_mfma_f32_32x32x16_bf16 v[80:95], v[224:227], v[244:247], v[80:95]
	v_mfma_f32_32x32x16_bf16 v[64:79], v[224:227], v[248:251], v[64:79]
	s_waitcnt lgkmcnt(0)
	s_waitcnt vmcnt(0)
	s_barrier
	s_add_u32 m0, s100, 0x6000
	v_lshl_add_u64 v[106:107], v[174:175], 0, s[96:97]
	global_load_lds_dwordx4 v[106:107], off
	s_add_u32 m0, s100, 0x7000
	v_lshl_add_u64 v[106:107], v[174:175], 0, s[50:51]
	global_load_lds_dwordx4 v[106:107], off
	ds_read_b128 v[236:239], v166 offset:49152
	ds_read_b128 v[240:243], v166 offset:53248
	ds_read_b128 v[224:227], v162
	v_mfma_f32_32x32x16_bf16 v[48:63], v[228:231], v[244:247], v[48:63]
	v_mfma_f32_32x32x16_bf16 v[32:47], v[228:231], v[248:251], v[32:47]
	ds_read_b128 v[228:231], v162 offset:4096
	v_mfma_f32_32x32x16_bf16 v[16:31], v[232:235], v[244:247], v[16:31]
	v_mfma_f32_32x32x16_bf16 v[0:15], v[232:235], v[248:251], v[0:15]
	s_add_u32 s15, s15, 2
	s_branch .Lga_loop

; template <int EPI, int MI>
; DI void gemm_tile(const GemmDesc& g, int tm, int tn, char* smem) {
;     ...
;   const int tid = get_tid(), lane = tid & 63, wave = tid >> 6, r = lane & 31, hh = lane >> 5;
;   const int wm = wave >> 1, wn = wave & 1;
;   const int m0 = tm * BM, n0 = tn * 128;
;   const int nk = g.K >> 6;
;   f32x16 acc[MI][2];
; #pragma unroll
;   for (int a = 0; a < MI; ++a)
; #pragma unroll
;     for (int b = 0; b < 2; ++b)
; #pragma unroll
;       for (int i = 0; i < 16; ++i) acc[a][b][i] = 0.f;
;   const int srow = tid >> 3;
;   const int schunk = (tid & 7) ^ ((srow & 7) ^ ((srow >> 3) & 3));
;     ...
;   const int rowA = wm * (32 * MI) + r, rowB = wn * 64 + r;
;   const int hk = hh ^ ((r & 7) ^ ((r >> 3) & 3));
;     ...
;   G_GLDS(0, 0);
;   asm volatile("s_waitcnt vmcnt(0)" ::: "memory");
;   __syncthreads();
; template <int EPI, int MI>
; DI void gemm_phase(const GemmDesc& g, char* smem, int vb, int nvb) {
;     ...
;   const int mPer = xm ? (g.nM >> 3) : g.nM;
;   const int PM = (mPer % 9 == 0) ? 9 : ((mPer & 7) == 0 ? 8 : ((mPer % 6) == 0 ? 6 : mPer));
;   const int per = PM * g.nN;
;   const int local = mPer * g.nN;
;   const int start = xm ? (vb >> 3) : vb, step = xm ? (nvb >> 3) : nvb;
;   const int mbase = xm ? xcd * mPer : 0;
;   for (int q = start; q < local; q += step) {
;     const int mg = q / per;
;     const int rem = q - mg * per;
;     const int tn = rem / PM;
;     const int tm = mbase + mg * PM + (rem - tn * PM);
.LBB0_254:
	s_abs_i32 s0, s42
	v_readlane_b32 s1, v219, 48
	s_mul_hi_u32 s1, s0, s1
	v_readlane_b32 s17, v219, 47
	s_mul_i32 s4, s1, s17
	s_sub_i32 s0, s0, s4
	s_ashr_i32 s15, s42, 31
	s_add_i32 s4, s1, 1
	s_sub_i32 s5, s0, s17
	s_cmp_ge_u32 s0, s17
	s_cselect_b32 s1, s4, s1
	s_cselect_b32 s0, s5, s0
	s_add_i32 s4, s1, 1
	s_cmp_ge_u32 s0, s17
	s_cselect_b32 s0, s4, s1
	s_xor_b32 s16, s0, s15
	s_sub_i32 s0, s16, s15
	s_mul_i32 s1, s0, s17
	s_sub_i32 s1, s42, s1
	s_abs_i32 s4, s1
	v_readlane_b32 s5, v219, 46
	s_mul_hi_u32 s5, s4, s5
	v_readlane_b32 s43, v218, 32
	s_mul_i32 s18, s5, s43
	s_sub_i32 s4, s4, s18
	s_ashr_i32 s17, s1, 31
	s_add_i32 s18, s5, 1
	s_sub_i32 s19, s4, s43
	s_cmp_ge_u32 s4, s43
	s_cselect_b32 s5, s18, s5
	s_cselect_b32 s4, s19, s4
	s_add_i32 s18, s5, 1
	s_cmp_ge_u32 s4, s43
	s_cselect_b32 s4, s18, s5
	s_xor_b32 s18, s4, s17
	v_mov_b32_e32 v97, v132
	s_sub_i32 s4, s18, s17
	s_mul_i32 s0, s0, s43
	v_ashrrev_i32_e32 v6, 3, v97
	s_mul_i32 s5, s4, s43
	s_waitcnt vmcnt(8)
	v_ashrrev_i32_e32 v109, 7, v97
	v_bfe_u32 v1, v97, 6, 2
	v_xor_b32_e32 v2, v6, v97
	s_add_i32 s0, s0, s54
	s_sub_i32 s1, s1, s5
	v_and_b32_e32 v108, 31, v97
	v_bitop3_b32 v2, v2, v1, 7 bitop3:0x6c
	v_mul_lo_u32 v1, v109, s6
	s_add_i32 s1, s0, s1
	s_lshl_b32 s0, s4, 7
	v_and_b32_e32 v0, 7, v97
	v_or_b32_e32 v7, v1, v108
	v_lshrrev_b32_e32 v1, 3, v97
	v_readlane_b32 s4, v221, 5
	s_mul_i32 s43, s1, 0xc0
	v_bfe_u32 v115, v97, 5, 1
	v_bitop3_b32 v0, v1, v0, 3 bitop3:0x6c
	v_readlane_b32 s5, v221, 6
	v_xor_b32_e32 v8, v0, v115
	v_add_u32_e32 v3, s43, v6
	v_mov_b64_e32 v[0:1], s[4:5]
	s_movk_i32 s19, 0x1600
	v_mad_i64_i32 v[0:1], s[4:5], v3, s19, v[0:1]
	v_readlane_b32 s4, v221, 10
	v_readlane_b32 s5, v221, 11
	v_lshlrev_b32_e32 v98, 4, v2
	v_add_u32_e32 v9, s0, v6
	v_mov_b64_e32 v[2:3], s[4:5]
	v_lshlrev_b32_e32 v120, 4, v97
	v_mad_i64_i32 v[2:3], s[4:5], v9, s19, v[2:3]
	v_add_u32_e32 v121, 0, v120
	v_mov_b32_e32 v99, v96
	v_readfirstlane_b32 s4, v121
	v_add_u32_e32 v122, 0x1000, v121
	v_lshl_add_u64 v[0:1], v[0:1], 0, v[98:99]
	s_mov_b32 m0, s4
	s_mov_b64 s[44:45], 0x2c000
	v_readfirstlane_b32 s4, v122
	v_add_u32_e32 v123, 0x2000, v121
	global_load_lds_dwordx4 v[0:1], off
	v_lshl_add_u64 v[4:5], v[0:1], 0, s[44:45]
	s_mov_b32 m0, s4
	s_mov_b64 s[46:47], 0x58000
	v_readfirstlane_b32 s4, v123
	v_add_u32_e32 v124, 0x3000, v121
	global_load_lds_dwordx4 v[4:5], off
	v_lshl_add_u64 v[4:5], v[0:1], 0, s[46:47]
	s_mov_b32 m0, s4
	s_mov_b64 s[52:53], 0x84000
	v_readfirstlane_b32 s4, v124
	global_load_lds_dwordx4 v[4:5], off
	v_lshl_add_u64 v[4:5], v[0:1], 0, s[52:53]
	s_mov_b32 m0, s4
	s_mov_b64 s[4:5], 0xb0000
	v_add_u32_e32 v125, 0x4000, v121
	global_load_lds_dwordx4 v[4:5], off
	v_lshl_add_u64 v[4:5], v[0:1], 0, s[4:5]
	v_readfirstlane_b32 s4, v125
	s_mov_b32 m0, s4
	s_mov_b64 s[4:5], 0xdc000
	v_add_u32_e32 v126, 0x5000, v121
	v_lshl_add_u64 v[0:1], v[0:1], 0, s[4:5]
	v_readfirstlane_b32 s4, v126
	v_add_u32_e32 v127, 0xc000, v121
	global_load_lds_dwordx4 v[4:5], off
	s_mov_b32 m0, s4
	v_readfirstlane_b32 s4, v127
	v_add_u32_e32 v128, 0xd000, v121
	global_load_lds_dwordx4 v[0:1], off
	v_lshl_add_u64 v[0:1], v[2:3], 0, v[98:99]
	s_mov_b32 m0, s4
	v_readfirstlane_b32 s4, v128
	v_add_u32_e32 v129, 0xe000, v121
	global_load_lds_dwordx4 v[0:1], off
	v_lshl_add_u64 v[2:3], v[0:1], 0, s[44:45]
	s_mov_b32 m0, s4
	v_readfirstlane_b32 s4, v129
	v_add_u32_e32 v130, 0xf000, v121
	global_load_lds_dwordx4 v[2:3], off
	v_lshl_add_u64 v[2:3], v[0:1], 0, s[46:47]
	s_mov_b32 m0, s4
	v_readfirstlane_b32 s4, v130
	global_load_lds_dwordx4 v[2:3], off
	v_lshl_add_u64 v[0:1], v[0:1], 0, s[52:53]
	s_mov_b32 m0, s4
	s_mul_i32 s15, s15, 7
	global_load_lds_dwordx4 v[0:1], off
	s_add_i32 s17, s17, s15
	s_sub_i32 s4, s17, s18
	s_mul_i32 s16, s16, 7
	s_sub_i32 s4, s4, s16
	v_readlane_b32 s5, v218, 33
	v_lshlrev_b32_e32 v0, 7, v97
	s_mul_i32 s4, s5, s4
	v_and_b32_e32 v0, 0x2f80, v0
	s_add_i32 s4, s4, s39
	s_waitcnt vmcnt(0)
	v_add_u32_e32 v153, 0, v0
	v_add_u32_e32 v155, s10, v0
	v_add_u32_e32 v2, s4, v6
	v_mov_b64_e32 v[0:1], s[70:71]
	v_lshlrev_b32_e32 v154, 4, v8
	v_mad_i64_i32 v[100:101], s[4:5], v2, s19, v[0:1]
	v_mad_i64_i32 v[102:103], s[4:5], v9, s19, v[0:1]
	v_mov_b32_e32 v0, 0
	v_lshl_add_u32 v131, v7, 7, 0
	v_xor_b32_e32 v156, 32, v154
	v_xor_b32_e32 v157, 64, v154
	v_xor_b32_e32 v158, 0x60, v154
	s_mov_b32 s15, 0
	v_mov_b32_e32 v1, v0
	v_mov_b32_e32 v2, v0
	v_mov_b32_e32 v3, v0
	v_mov_b32_e32 v4, v0
	v_mov_b32_e32 v5, v0
	v_mov_b32_e32 v6, v0
	v_mov_b32_e32 v7, v0
	v_mov_b32_e32 v8, v0
	v_mov_b32_e32 v9, v0
	v_mov_b32_e32 v10, v0
	v_mov_b32_e32 v11, v0
	v_mov_b32_e32 v12, v0
	v_mov_b32_e32 v13, v0
	v_mov_b32_e32 v14, v0
	v_mov_b32_e32 v15, v0
	v_mov_b32_e32 v16, v0
	v_mov_b32_e32 v17, v0
	v_mov_b32_e32 v18, v0
	v_mov_b32_e32 v19, v0
	v_mov_b32_e32 v20, v0
	v_mov_b32_e32 v21, v0
	v_mov_b32_e32 v22, v0
	v_mov_b32_e32 v23, v0
	v_mov_b32_e32 v24, v0
	v_mov_b32_e32 v25, v0
	v_mov_b32_e32 v26, v0
	v_mov_b32_e32 v27, v0
	v_mov_b32_e32 v28, v0
	v_mov_b32_e32 v29, v0
	v_mov_b32_e32 v30, v0
	v_mov_b32_e32 v31, v0
	v_mov_b32_e32 v32, v0
	v_mov_b32_e32 v33, v0
	v_mov_b32_e32 v34, v0
	v_mov_b32_e32 v35, v0
	v_mov_b32_e32 v36, v0
	v_mov_b32_e32 v37, v0
	v_mov_b32_e32 v38, v0
	v_mov_b32_e32 v39, v0
	v_mov_b32_e32 v40, v0
	v_mov_b32_e32 v41, v0
	v_mov_b32_e32 v42, v0
	v_mov_b32_e32 v43, v0
	v_mov_b32_e32 v44, v0
	v_mov_b32_e32 v45, v0
	v_mov_b32_e32 v46, v0
	v_mov_b32_e32 v47, v0
	v_mov_b32_e32 v48, v0
	s_waitcnt vmcnt(0)
; template <int EPI, int MI>
; DI void gemm_tile(const GemmDesc& g, int tm, int tn, char* smem) {
;     ...
;   f32x16 acc[MI][2];
; #pragma unroll
;   for (int a = 0; a < MI; ++a)
; #pragma unroll
;     for (int b = 0; b < 2; ++b)
; #pragma unroll
;       for (int i = 0; i < 16; ++i) acc[a][b][i] = 0.f;
;   const int srow = tid >> 3;
;   const int schunk = (tid & 7) ^ ((srow & 7) ^ ((srow >> 3) & 3));
;     ...
;   const int rowA = wm * (32 * MI) + r, rowB = wn * 64 + r;
;   const int hk = hh ^ ((r & 7) ^ ((r >> 3) & 3));
;     ...
;   G_GLDS(0, 0);
;   asm volatile("s_waitcnt vmcnt(0)" ::: "memory");
;   __syncthreads();
;   for (int kt = 0; kt < nk; kt += 2) {
;     if (kt + 1 < nk) G_GLDS(kt + 1, 1);
;     G_COMPUTE(0);
;     asm volatile("s_waitcnt vmcnt(0)" ::: "memory");
;     __syncthreads();
;     if (kt + 1 < nk) {
;       if (kt + 2 < nk) G_GLDS(kt + 2, 0);
;       G_COMPUTE(1);
;       asm volatile("s_waitcnt vmcnt(0)" ::: "memory");
;       __syncthreads();
;     }
;   }
	v_mov_b32_e32 v49, v0
	v_mov_b32_e32 v50, v0
	v_mov_b32_e32 v51, v0
	v_mov_b32_e32 v52, v0
	v_mov_b32_e32 v53, v0
	v_mov_b32_e32 v54, v0
	v_mov_b32_e32 v55, v0
	v_mov_b32_e32 v56, v0
	v_mov_b32_e32 v57, v0
	v_mov_b32_e32 v58, v0
	v_mov_b32_e32 v59, v0
	v_mov_b32_e32 v60, v0
	v_mov_b32_e32 v61, v0
	v_mov_b32_e32 v62, v0
	v_mov_b32_e32 v63, v0
	v_mov_b32_e32 v64, v0
	v_mov_b32_e32 v65, v0
	v_mov_b32_e32 v66, v0
	v_mov_b32_e32 v67, v0
	v_mov_b32_e32 v68, v0
	v_mov_b32_e32 v69, v0
	v_mov_b32_e32 v70, v0
	v_mov_b32_e32 v71, v0
	v_mov_b32_e32 v72, v0
	v_mov_b32_e32 v73, v0
	v_mov_b32_e32 v74, v0
	v_mov_b32_e32 v75, v0
	v_mov_b32_e32 v76, v0
	v_mov_b32_e32 v77, v0
	v_mov_b32_e32 v78, v0
	v_mov_b32_e32 v79, v0
	v_mov_b32_e32 v80, v0
	v_mov_b32_e32 v81, v0
	v_mov_b32_e32 v82, v0
	v_mov_b32_e32 v83, v0
	v_mov_b32_e32 v84, v0
	v_mov_b32_e32 v85, v0
	v_mov_b32_e32 v86, v0
	v_mov_b32_e32 v87, v0
	v_mov_b32_e32 v88, v0
	v_mov_b32_e32 v89, v0
	v_mov_b32_e32 v90, v0
	v_mov_b32_e32 v91, v0
	v_mov_b32_e32 v92, v0
	v_mov_b32_e32 v93, v0
	v_mov_b32_e32 v94, v0
	v_mov_b32_e32 v95, v0
	v_add_u32_e32 v162, v131, v154
	v_add_u32_e32 v163, v131, v156
	v_add_u32_e32 v164, v131, v157
	v_add_u32_e32 v165, v131, v158
	v_add_u32_e32 v166, v153, v154
	v_add_u32_e32 v167, v153, v156
	v_add_u32_e32 v168, v153, v157
	v_add_u32_e32 v169, v153, v158
	v_add_u32_e32 v170, v155, v154
	v_add_u32_e32 v171, v155, v156
	v_add_u32_e32 v172, v155, v157
	v_add_u32_e32 v173, v155, v158
	v_lshl_add_u64 v[252:253], v[100:101], 0, v[98:99]
	v_lshl_add_u64 v[254:255], v[102:103], 0, v[98:99]
	v_readfirstlane_b32 s100, v121
	s_mov_b64 s[4:5], 0x80
	s_waitcnt vmcnt(0) lgkmcnt(0)
	s_barrier
	s_mov_b64 s[16:17], 0x5872080
	s_add_u32 m0, s100, 0x6000
	v_lshl_add_u64 v[106:107], v[252:253], 0, s[16:17]
	global_load_lds_dwordx4 v[106:107], off
	s_mov_b64 s[16:17], 0x589e080
	s_add_u32 m0, s100, 0x7000
	v_lshl_add_u64 v[106:107], v[252:253], 0, s[16:17]
	global_load_lds_dwordx4 v[106:107], off
	ds_read_b128 v[236:239], v166 offset:49152
	ds_read_b128 v[240:243], v166 offset:53248
	ds_read_b128 v[224:227], v162
	ds_read_b128 v[228:231], v162 offset:4096
	s_mov_b32 s15, 0
.Lgd_loop:
	ds_read_b128 v[232:235], v162 offset:8192
	s_waitcnt lgkmcnt(2)
	v_mfma_f32_32x32x16_bf16 v[80:95], v[224:227], v[236:239], v[80:95]
	v_mfma_f32_32x32x16_bf16 v[64:79], v[224:227], v[240:243], v[64:79]
	ds_read_b128 v[244:247], v167 offset:49152
	ds_read_b128 v[248:251], v167 offset:53248
	ds_read_b128 v[224:227], v163
	s_waitcnt lgkmcnt(4)
	v_mfma_f32_32x32x16_bf16 v[48:63], v[228:231], v[236:239], v[48:63]
	v_mfma_f32_32x32x16_bf16 v[32:47], v[228:231], v[240:243], v[32:47]
	s_mov_b64 s[16:17], 0x58ca080
	s_add_u32 m0, s100, 0x8000
	v_lshl_add_u64 v[106:107], v[252:253], 0, s[16:17]
	global_load_lds_dwordx4 v[106:107], off
	s_mov_b64 s[16:17], 0x58f6080
	s_add_u32 m0, s100, 0x9000
	v_lshl_add_u64 v[106:107], v[252:253], 0, s[16:17]
	global_load_lds_dwordx4 v[106:107], off
	ds_read_b128 v[228:231], v163 offset:4096
	s_waitcnt lgkmcnt(4)
	v_mfma_f32_32x32x16_bf16 v[16:31], v[232:235], v[236:239], v[16:31]
	v_mfma_f32_32x32x16_bf16 v[0:15], v[232:235], v[240:243], v[0:15]
	s_mov_b64 s[16:17], 0x5922080
	s_add_u32 m0, s100, 0xa000
	v_lshl_add_u64 v[106:107], v[252:253], 0, s[16:17]
	global_load_lds_dwordx4 v[106:107], off
	s_mov_b64 s[16:17], 0x594e080
	s_add_u32 m0, s100, 0xb000
	v_lshl_add_u64 v[106:107], v[252:253], 0, s[16:17]
	global_load_lds_dwordx4 v[106:107], off
	v_lshl_add_u64 v[252:253], v[252:253], 0, s[4:5]
	ds_read_b128 v[232:235], v163 offset:8192
	s_waitcnt lgkmcnt(2)
	v_mfma_f32_32x32x16_bf16 v[80:95], v[224:227], v[244:247], v[80:95]
	v_mfma_f32_32x32x16_bf16 v[64:79], v[224:227], v[248:251], v[64:79]
	s_mov_b64 s[16:17], 0x1600080
	s_add_u32 m0, s100, 0x10000
	v_lshl_add_u64 v[106:107], v[254:255], 0, s[16:17]
	global_load_lds_dwordx4 v[106:107], off
	s_mov_b64 s[16:17], 0x162c080
	s_add_u32 m0, s100, 0x11000
	v_lshl_add_u64 v[106:107], v[254:255], 0, s[16:17]
	global_load_lds_dwordx4 v[106:107], off
	ds_read_b128 v[236:239], v168 offset:49152
	ds_read_b128 v[240:243], v168 offset:53248
	ds_read_b128 v[224:227], v164
	s_waitcnt lgkmcnt(4)
	v_mfma_f32_32x32x16_bf16 v[48:63], v[228:231], v[244:247], v[48:63]
	v_mfma_f32_32x32x16_bf16 v[32:47], v[228:231], v[248:251], v[32:47]
	s_mov_b64 s[16:17], 0x1658080
	s_add_u32 m0, s100, 0x12000
	v_lshl_add_u64 v[106:107], v[254:255], 0, s[16:17]
	global_load_lds_dwordx4 v[106:107], off
	s_mov_b64 s[16:17], 0x1684080
	s_add_u32 m0, s100, 0x13000
	v_lshl_add_u64 v[106:107], v[254:255], 0, s[16:17]
	global_load_lds_dwordx4 v[106:107], off
	v_lshl_add_u64 v[254:255], v[254:255], 0, s[4:5]
	ds_read_b128 v[228:231], v164 offset:4096
	s_waitcnt lgkmcnt(4)
	v_mfma_f32_32x32x16_bf16 v[16:31], v[232:235], v[244:247], v[16:31]
	v_mfma_f32_32x32x16_bf16 v[0:15], v[232:235], v[248:251], v[0:15]
	ds_read_b128 v[232:235], v164 offset:8192
	s_waitcnt lgkmcnt(2)
	v_mfma_f32_32x32x16_bf16 v[80:95], v[224:227], v[236:239], v[80:95]
	v_mfma_f32_32x32x16_bf16 v[64:79], v[224:227], v[240:243], v[64:79]
	ds_read_b128 v[244:247], v169 offset:49152
	ds_read_b128 v[248:251], v169 offset:53248
	ds_read_b128 v[224:227], v165
	s_waitcnt lgkmcnt(4)
	v_mfma_f32_32x32x16_bf16 v[48:63], v[228:231], v[236:239], v[48:63]
	v_mfma_f32_32x32x16_bf16 v[32:47], v[228:231], v[240:243], v[32:47]
	ds_read_b128 v[228:231], v165 offset:4096
	s_waitcnt lgkmcnt(4)
	v_mfma_f32_32x32x16_bf16 v[16:31], v[232:235], v[236:239], v[16:31]
	v_mfma_f32_32x32x16_bf16 v[0:15], v[232:235], v[240:243], v[0:15]
	ds_read_b128 v[232:235], v165 offset:8192
	s_waitcnt lgkmcnt(2)
	v_mfma_f32_32x32x16_bf16 v[80:95], v[224:227], v[244:247], v[80:95]
	v_mfma_f32_32x32x16_bf16 v[64:79], v[224:227], v[248:251], v[64:79]
	s_waitcnt lgkmcnt(0)
	s_waitcnt vmcnt(0)
	s_barrier
	s_cmp_eq_u32 s15, 42
	s_cbranch_scc1 .Lgd_noearly
	s_mov_b64 s[16:17], 0x5872080
	s_mov_b32 m0, s100
	v_lshl_add_u64 v[106:107], v[252:253], 0, s[16:17]
	global_load_lds_dwordx4 v[106:107], off
	s_mov_b64 s[16:17], 0x589e080
	s_add_u32 m0, s100, 0x1000
	v_lshl_add_u64 v[106:107], v[252:253], 0, s[16:17]
	global_load_lds_dwordx4 v[106:107], off
; template <int EPI, int MI>
; DI void gemm_tile(const GemmDesc& g, int tm, int tn, char* smem) {
;     ...
;   const int rowA = wm * (32 * MI) + r, rowB = wn * 64 + r;
;   const int hk = hh ^ ((r & 7) ^ ((r >> 3) & 3));
;     ...
;   G_GLDS(0, 0);
;   asm volatile("s_waitcnt vmcnt(0)" ::: "memory");
;   __syncthreads();
;   for (int kt = 0; kt < nk; kt += 2) {
;     if (kt + 1 < nk) G_GLDS(kt + 1, 1);
;     G_COMPUTE(0);
;     asm volatile("s_waitcnt vmcnt(0)" ::: "memory");
;     __syncthreads();
;     if (kt + 1 < nk) {
;       if (kt + 2 < nk) G_GLDS(kt + 2, 0);
;       G_COMPUTE(1);
;       asm volatile("s_waitcnt vmcnt(0)" ::: "memory");
;       __syncthreads();
;     }
;   }
.Lgd_noearly:
	ds_read_b128 v[236:239], v170
	ds_read_b128 v[240:243], v170 offset:4096
	ds_read_b128 v[224:227], v162 offset:24576
	v_mfma_f32_32x32x16_bf16 v[48:63], v[228:231], v[244:247], v[48:63]
	v_mfma_f32_32x32x16_bf16 v[32:47], v[228:231], v[248:251], v[32:47]
	ds_read_b128 v[228:231], v162 offset:28672
	v_mfma_f32_32x32x16_bf16 v[16:31], v[232:235], v[244:247], v[16:31]
	v_mfma_f32_32x32x16_bf16 v[0:15], v[232:235], v[248:251], v[0:15]
	s_cmp_eq_u32 s15, 42
	s_cbranch_scc1 .Lgd_last
	ds_read_b128 v[232:235], v162 offset:32768
	s_waitcnt lgkmcnt(2)
	v_mfma_f32_32x32x16_bf16 v[80:95], v[224:227], v[236:239], v[80:95]
	v_mfma_f32_32x32x16_bf16 v[64:79], v[224:227], v[240:243], v[64:79]
	ds_read_b128 v[244:247], v171
	ds_read_b128 v[248:251], v171 offset:4096
	ds_read_b128 v[224:227], v163 offset:24576
	s_waitcnt lgkmcnt(4)
	v_mfma_f32_32x32x16_bf16 v[48:63], v[228:231], v[236:239], v[48:63]
	v_mfma_f32_32x32x16_bf16 v[32:47], v[228:231], v[240:243], v[32:47]
	s_mov_b64 s[16:17], 0x58ca080
	s_add_u32 m0, s100, 0x2000
	v_lshl_add_u64 v[106:107], v[252:253], 0, s[16:17]
	global_load_lds_dwordx4 v[106:107], off
	s_mov_b64 s[16:17], 0x58f6080
	s_add_u32 m0, s100, 0x3000
	v_lshl_add_u64 v[106:107], v[252:253], 0, s[16:17]
	global_load_lds_dwordx4 v[106:107], off
	ds_read_b128 v[228:231], v163 offset:28672
	s_waitcnt lgkmcnt(4)
	v_mfma_f32_32x32x16_bf16 v[16:31], v[232:235], v[236:239], v[16:31]
	v_mfma_f32_32x32x16_bf16 v[0:15], v[232:235], v[240:243], v[0:15]
	s_mov_b64 s[16:17], 0x5922080
	s_add_u32 m0, s100, 0x4000
	v_lshl_add_u64 v[106:107], v[252:253], 0, s[16:17]
	global_load_lds_dwordx4 v[106:107], off
	s_mov_b64 s[16:17], 0x594e080
	s_add_u32 m0, s100, 0x5000
	v_lshl_add_u64 v[106:107], v[252:253], 0, s[16:17]
	global_load_lds_dwordx4 v[106:107], off
	v_lshl_add_u64 v[252:253], v[252:253], 0, s[4:5]
	ds_read_b128 v[232:235], v163 offset:32768
	s_waitcnt lgkmcnt(2)
	v_mfma_f32_32x32x16_bf16 v[80:95], v[224:227], v[244:247], v[80:95]
	v_mfma_f32_32x32x16_bf16 v[64:79], v[224:227], v[248:251], v[64:79]
	s_mov_b64 s[16:17], 0x1600080
	s_add_u32 m0, s100, 0xc000
	v_lshl_add_u64 v[106:107], v[254:255], 0, s[16:17]
	global_load_lds_dwordx4 v[106:107], off
	s_mov_b64 s[16:17], 0x162c080
	s_add_u32 m0, s100, 0xd000
	v_lshl_add_u64 v[106:107], v[254:255], 0, s[16:17]
	global_load_lds_dwordx4 v[106:107], off
	ds_read_b128 v[236:239], v172
	ds_read_b128 v[240:243], v172 offset:4096
	ds_read_b128 v[224:227], v164 offset:24576
	s_waitcnt lgkmcnt(4)
	v_mfma_f32_32x32x16_bf16 v[48:63], v[228:231], v[244:247], v[48:63]
	v_mfma_f32_32x32x16_bf16 v[32:47], v[228:231], v[248:251], v[32:47]
	s_mov_b64 s[16:17], 0x1658080
	s_add_u32 m0, s100, 0xe000
	v_lshl_add_u64 v[106:107], v[254:255], 0, s[16:17]
	global_load_lds_dwordx4 v[106:107], off
	s_mov_b64 s[16:17], 0x1684080
	s_add_u32 m0, s100, 0xf000
	v_lshl_add_u64 v[106:107], v[254:255], 0, s[16:17]
	global_load_lds_dwordx4 v[106:107], off
	v_lshl_add_u64 v[254:255], v[254:255], 0, s[4:5]
	ds_read_b128 v[228:231], v164 offset:28672
	s_waitcnt lgkmcnt(4)
	v_mfma_f32_32x32x16_bf16 v[16:31], v[232:235], v[244:247], v[16:31]
	v_mfma_f32_32x32x16_bf16 v[0:15], v[232:235], v[248:251], v[0:15]
	ds_read_b128 v[232:235], v164 offset:32768
	s_waitcnt lgkmcnt(2)
	v_mfma_f32_32x32x16_bf16 v[80:95], v[224:227], v[236:239], v[80:95]
	v_mfma_f32_32x32x16_bf16 v[64:79], v[224:227], v[240:243], v[64:79]
	ds_read_b128 v[244:247], v173
	ds_read_b128 v[248:251], v173 offset:4096
	ds_read_b128 v[224:227], v165 offset:24576
	s_waitcnt lgkmcnt(4)
	v_mfma_f32_32x32x16_bf16 v[48:63], v[228:231], v[236:239], v[48:63]
	v_mfma_f32_32x32x16_bf16 v[32:47], v[228:231], v[240:243], v[32:47]
	ds_read_b128 v[228:231], v165 offset:28672
	s_waitcnt lgkmcnt(4)
	v_mfma_f32_32x32x16_bf16 v[16:31], v[232:235], v[236:239], v[16:31]
	v_mfma_f32_32x32x16_bf16 v[0:15], v[232:235], v[240:243], v[0:15]
	ds_read_b128 v[232:235], v165 offset:32768
	s_waitcnt lgkmcnt(2)
	v_mfma_f32_32x32x16_bf16 v[80:95], v[224:227], v[244:247], v[80:95]
	v_mfma_f32_32x32x16_bf16 v[64:79], v[224:227], v[248:251], v[64:79]
	s_waitcnt lgkmcnt(0)
	s_waitcnt vmcnt(0)
	s_barrier
	s_mov_b64 s[16:17], 0x5872080
	s_add_u32 m0, s100, 0x6000
	v_lshl_add_u64 v[106:107], v[252:253], 0, s[16:17]
	global_load_lds_dwordx4 v[106:107], off
	s_mov_b64 s[16:17], 0x589e080
	s_add_u32 m0, s100, 0x7000
	v_lshl_add_u64 v[106:107], v[252:253], 0, s[16:17]
	global_load_lds_dwordx4 v[106:107], off
	ds_read_b128 v[236:239], v166 offset:49152
	ds_read_b128 v[240:243], v166 offset:53248
	ds_read_b128 v[224:227], v162
	v_mfma_f32_32x32x16_bf16 v[48:63], v[228:231], v[244:247], v[48:63]
	v_mfma_f32_32x32x16_bf16 v[32:47], v[228:231], v[248:251], v[32:47]
	ds_read_b128 v[228:231], v162 offset:4096
	v_mfma_f32_32x32x16_bf16 v[16:31], v[232:235], v[244:247], v[16:31]
	v_mfma_f32_32x32x16_bf16 v[0:15], v[232:235], v[248:251], v[0:15]
	s_add_u32 s15, s15, 2
	s_branch .Lgd_loop

; template <int EPI, int MI>
; DI void gemm_tile(const GemmDesc& g, int tm, int tn, char* smem) {
;     ...
;   const int tid = get_tid(), lane = tid & 63, wave = tid >> 6, r = lane & 31, hh = lane >> 5;
;   const int wm = wave >> 1, wn = wave & 1;
;   const int m0 = tm * BM, n0 = tn * 128;
;   const int nk = g.K >> 6;
;   f32x16 acc[MI][2];
; #pragma unroll
;   for (int a = 0; a < MI; ++a)
; #pragma unroll
;     for (int b = 0; b < 2; ++b)
; #pragma unroll
;       for (int i = 0; i < 16; ++i) acc[a][b][i] = 0.f;
;   const int srow = tid >> 3;
;   const int schunk = (tid & 7) ^ ((srow & 7) ^ ((srow >> 3) & 3));
;     ...
;   const int rowA = wm * (32 * MI) + r, rowB = wn * 64 + r;
;   const int hk = hh ^ ((r & 7) ^ ((r >> 3) & 3));
;     ...
;   G_GLDS(0, 0);
;   asm volatile("s_waitcnt vmcnt(0)" ::: "memory");
;   __syncthreads();
; template <int EPI, int MI>
; DI void gemm_phase(const GemmDesc& g, char* smem, int vb, int nvb) {
;     ...
;   const int mPer = xm ? (g.nM >> 3) : g.nM;
;   const int PM = (mPer % 9 == 0) ? 9 : ((mPer & 7) == 0 ? 8 : ((mPer % 6) == 0 ? 6 : mPer));
;   const int per = PM * g.nN;
;   const int local = mPer * g.nN;
;   const int start = xm ? (vb >> 3) : vb, step = xm ? (nvb >> 3) : nvb;
;   const int mbase = xm ? xcd * mPer : 0;
;   for (int q = start; q < local; q += step) {
;     const int mg = q / per;
;     const int rem = q - mg * per;
;     const int tn = rem / PM;
;     const int tm = mbase + mg * PM + (rem - tn * PM);
.LBB0_371:
	s_abs_i32 s1, s47
	s_mul_hi_u32 s4, s1, s45
	s_mul_i32 s5, s4, s43
	s_sub_i32 s1, s1, s5
	s_ashr_i32 s0, s47, 31
	s_add_i32 s5, s4, 1
	s_sub_i32 s15, s1, s43
	s_cmp_ge_u32 s1, s43
	s_cselect_b32 s4, s5, s4
	s_cselect_b32 s1, s15, s1
	s_add_i32 s5, s4, 1
	s_cmp_ge_u32 s1, s43
	s_cselect_b32 s1, s5, s4
	s_xor_b32 s1, s1, s0
	s_sub_i32 s4, s1, s0
	s_mul_i32 s5, s4, s43
	s_sub_i32 s5, s47, s5
	s_abs_i32 s16, s5
	v_readlane_b32 s17, v219, 46
	s_mul_hi_u32 s17, s16, s17
	v_readlane_b32 s38, v218, 32
	s_mul_i32 s18, s17, s38
	s_sub_i32 s16, s16, s18
	s_ashr_i32 s15, s5, 31
	s_add_i32 s18, s17, 1
	s_sub_i32 s19, s16, s38
	s_cmp_ge_u32 s16, s38
	s_cselect_b32 s17, s18, s17
	s_cselect_b32 s16, s19, s16
	s_add_i32 s18, s17, 1
	s_cmp_ge_u32 s16, s38
	s_cselect_b32 s16, s18, s17
	s_xor_b32 s16, s16, s15
	s_sub_i32 s17, s16, s15
	s_sub_i32 s18, s4, s17
	v_mov_b32_e32 v97, v132
	s_mul_i32 s18, s18, s38
	s_add_i32 s5, s5, s54
	s_add_i32 s48, s5, s18
	v_ashrrev_i32_e32 v0, 7, v97
	v_and_b32_e32 v1, 7, v97
	v_mul_lo_u32 v115, v0, s6
	v_lshrrev_b32_e32 v0, 3, v97
	s_mulk_i32 s48, 0xc0
	s_waitcnt vmcnt(8)
	v_bfe_u32 v109, v97, 5, 1
	v_ashrrev_i32_e32 v8, 3, v97
	v_bitop3_b32 v0, v0, v1, 3 bitop3:0x6c
	v_bfe_u32 v2, v97, 6, 2
	v_xor_b32_e32 v3, v8, v97
	v_xor_b32_e32 v10, v0, v109
	v_add_u32_e32 v0, s48, v8
	s_lshl_b32 s49, s17, 7
	v_bitop3_b32 v2, v3, v2, 7 bitop3:0x6c
	v_ashrrev_i32_e32 v1, 31, v0
	v_readlane_b32 s18, v223, 59
	v_lshlrev_b64 v[0:1], 11, v[0:1]
	v_readlane_b32 s19, v223, 60
	v_lshlrev_b32_e32 v98, 4, v2
	v_add_u32_e32 v2, s49, v8
	v_lshlrev_b32_e32 v120, 4, v97
	v_lshl_add_u64 v[0:1], s[18:19], 0, v[0:1]
	v_ashrrev_i32_e32 v3, 31, v2
	v_readlane_b32 s18, v221, 16
	v_add_u32_e32 v121, 0, v120
	v_mov_b32_e32 v99, v96
	v_lshlrev_b64 v[2:3], 11, v[2:3]
	v_readlane_b32 s19, v221, 17
	v_readfirstlane_b32 s5, v121
	v_add_u32_e32 v122, 0x1000, v121
	v_lshl_add_u64 v[0:1], v[0:1], 0, v[98:99]
	v_lshl_add_u64 v[4:5], s[18:19], 0, v[2:3]
	s_mov_b32 m0, s5
	s_mov_b64 s[18:19], 0x10000
	v_readfirstlane_b32 s5, v122
	v_add_u32_e32 v123, 0x2000, v121
	global_load_lds_dwordx4 v[0:1], off
	v_lshl_add_u64 v[6:7], v[0:1], 0, s[18:19]
	s_mov_b32 m0, s5
	s_mov_b64 s[38:39], 0x20000
	v_readfirstlane_b32 s5, v123
	v_add_u32_e32 v124, 0x3000, v121
	global_load_lds_dwordx4 v[6:7], off
	v_lshl_add_u64 v[6:7], v[0:1], 0, s[38:39]
	s_mov_b32 m0, s5
	s_mov_b64 s[52:53], 0x30000
	v_readfirstlane_b32 s5, v124
	v_add_u32_e32 v125, 0x4000, v121
	global_load_lds_dwordx4 v[6:7], off
	v_lshl_add_u64 v[6:7], v[0:1], 0, s[52:53]
	s_mov_b32 m0, s5
	s_mov_b64 s[72:73], 0x40000
	v_readfirstlane_b32 s5, v125
	v_add_u32_e32 v126, 0x5000, v121
	global_load_lds_dwordx4 v[6:7], off
	v_lshl_add_u64 v[6:7], v[0:1], 0, s[72:73]
	s_mov_b32 m0, s5
	s_mov_b64 s[72:73], 0x50000
	v_readfirstlane_b32 s5, v126
	v_add_u32_e32 v127, 0xc000, v121
	global_load_lds_dwordx4 v[6:7], off
	v_lshl_add_u64 v[0:1], v[0:1], 0, s[72:73]
	s_mov_b32 m0, s5
	v_readfirstlane_b32 s5, v127
	v_add_u32_e32 v128, 0xd000, v121
	global_load_lds_dwordx4 v[0:1], off
	v_lshl_add_u64 v[0:1], v[4:5], 0, v[98:99]
	s_mov_b32 m0, s5
	v_readfirstlane_b32 s5, v128
	v_add_u32_e32 v129, 0xe000, v121
	global_load_lds_dwordx4 v[0:1], off
	v_lshl_add_u64 v[4:5], v[0:1], 0, s[18:19]
	s_mov_b32 m0, s5
	v_readfirstlane_b32 s5, v129
	v_add_u32_e32 v130, 0xf000, v121
	global_load_lds_dwordx4 v[4:5], off
	v_lshl_add_u64 v[4:5], v[0:1], 0, s[38:39]
	s_mov_b32 m0, s5
	v_readfirstlane_b32 s5, v130
	global_load_lds_dwordx4 v[4:5], off
	v_lshl_add_u64 v[0:1], v[0:1], 0, s[52:53]
	s_mov_b32 m0, s5
	s_add_i32 s1, s1, s15
	global_load_lds_dwordx4 v[0:1], off
	s_mul_i32 s4, s20, s4
	s_sub_i32 s1, s1, s4
	s_sub_i32 s1, s1, s16
	s_sub_i32 s0, s1, s0
	v_readlane_b32 s1, v218, 33
	v_lshlrev_b32_e32 v0, 7, v97
	s_mul_i32 s0, s1, s0
	v_and_b32_e32 v0, 0x2f80, v0
	s_add_i32 s0, s0, s46
	v_add_u32_e32 v153, 0, v0
	v_add_u32_e32 v155, s10, v0
	v_add_u32_e32 v0, s0, v8
	v_ashrrev_i32_e32 v1, 31, v0
	v_and_b32_e32 v108, 31, v97
	s_waitcnt vmcnt(0)
	v_lshlrev_b64 v[0:1], 11, v[0:1]
	v_or_b32_e32 v9, v115, v108
	v_lshlrev_b32_e32 v154, 4, v10
	v_lshl_add_u64 v[102:103], s[70:71], 0, v[0:1]
	v_mov_b32_e32 v0, 0
	v_lshl_add_u32 v131, v9, 7, 0
	v_xor_b32_e32 v156, 32, v154
	v_xor_b32_e32 v157, 64, v154
	v_xor_b32_e32 v158, 0x60, v154
	v_lshl_add_u64 v[100:101], s[70:71], 0, v[2:3]
	s_mov_b32 s4, 0
	v_mov_b32_e32 v1, v0
	v_mov_b32_e32 v2, v0
	v_mov_b32_e32 v3, v0
	v_mov_b32_e32 v4, v0
	v_mov_b32_e32 v5, v0
	v_mov_b32_e32 v6, v0
	v_mov_b32_e32 v7, v0
	v_mov_b32_e32 v8, v0
	v_mov_b32_e32 v9, v0
	v_mov_b32_e32 v10, v0
	v_mov_b32_e32 v11, v0
	v_mov_b32_e32 v12, v0
	v_mov_b32_e32 v13, v0
	v_mov_b32_e32 v14, v0
	v_mov_b32_e32 v15, v0
	v_mov_b32_e32 v16, v0
	v_mov_b32_e32 v17, v0
	v_mov_b32_e32 v18, v0
	v_mov_b32_e32 v19, v0
	v_mov_b32_e32 v20, v0
	v_mov_b32_e32 v21, v0
	v_mov_b32_e32 v22, v0
	v_mov_b32_e32 v23, v0
	v_mov_b32_e32 v24, v0
	v_mov_b32_e32 v25, v0
	v_mov_b32_e32 v26, v0
	v_mov_b32_e32 v27, v0
	v_mov_b32_e32 v28, v0
	v_mov_b32_e32 v29, v0
	v_mov_b32_e32 v30, v0
	v_mov_b32_e32 v31, v0
	v_mov_b32_e32 v32, v0
	v_mov_b32_e32 v33, v0
	v_mov_b32_e32 v34, v0
	v_mov_b32_e32 v35, v0
	v_mov_b32_e32 v36, v0
	v_mov_b32_e32 v37, v0
	v_mov_b32_e32 v38, v0
	v_mov_b32_e32 v39, v0
	v_mov_b32_e32 v40, v0
	v_mov_b32_e32 v41, v0
	v_mov_b32_e32 v42, v0
	v_mov_b32_e32 v43, v0
	v_mov_b32_e32 v44, v0
	v_mov_b32_e32 v45, v0
	v_mov_b32_e32 v46, v0
	v_mov_b32_e32 v47, v0
	v_mov_b32_e32 v48, v0
	s_waitcnt vmcnt(0)
; template <int EPI, int MI>
; DI void gemm_tile(const GemmDesc& g, int tm, int tn, char* smem) {
;     ...
;   f32x16 acc[MI][2];
; #pragma unroll
;   for (int a = 0; a < MI; ++a)
; #pragma unroll
;     for (int b = 0; b < 2; ++b)
; #pragma unroll
;       for (int i = 0; i < 16; ++i) acc[a][b][i] = 0.f;
;   const int srow = tid >> 3;
;   const int schunk = (tid & 7) ^ ((srow & 7) ^ ((srow >> 3) & 3));
;     ...
;   const int rowA = wm * (32 * MI) + r, rowB = wn * 64 + r;
;   const int hk = hh ^ ((r & 7) ^ ((r >> 3) & 3));
;     ...
;   G_GLDS(0, 0);
;   asm volatile("s_waitcnt vmcnt(0)" ::: "memory");
;   __syncthreads();
;   for (int kt = 0; kt < nk; kt += 2) {
;     if (kt + 1 < nk) G_GLDS(kt + 1, 1);
;     G_COMPUTE(0);
;     asm volatile("s_waitcnt vmcnt(0)" ::: "memory");
;     __syncthreads();
;     if (kt + 1 < nk) {
;       if (kt + 2 < nk) G_GLDS(kt + 2, 0);
;       G_COMPUTE(1);
;       asm volatile("s_waitcnt vmcnt(0)" ::: "memory");
;       __syncthreads();
;     }
;   }
	v_mov_b32_e32 v49, v0
	v_mov_b32_e32 v50, v0
	v_mov_b32_e32 v51, v0
	v_mov_b32_e32 v52, v0
	v_mov_b32_e32 v53, v0
	v_mov_b32_e32 v54, v0
	v_mov_b32_e32 v55, v0
	v_mov_b32_e32 v56, v0
	v_mov_b32_e32 v57, v0
	v_mov_b32_e32 v58, v0
	v_mov_b32_e32 v59, v0
	v_mov_b32_e32 v60, v0
	v_mov_b32_e32 v61, v0
	v_mov_b32_e32 v62, v0
	v_mov_b32_e32 v63, v0
	v_mov_b32_e32 v64, v0
	v_mov_b32_e32 v65, v0
	v_mov_b32_e32 v66, v0
	v_mov_b32_e32 v67, v0
	v_mov_b32_e32 v68, v0
	v_mov_b32_e32 v69, v0
	v_mov_b32_e32 v70, v0
	v_mov_b32_e32 v71, v0
	v_mov_b32_e32 v72, v0
	v_mov_b32_e32 v73, v0
	v_mov_b32_e32 v74, v0
	v_mov_b32_e32 v75, v0
	v_mov_b32_e32 v76, v0
	v_mov_b32_e32 v77, v0
	v_mov_b32_e32 v78, v0
	v_mov_b32_e32 v79, v0
	v_mov_b32_e32 v80, v0
	v_mov_b32_e32 v81, v0
	v_mov_b32_e32 v82, v0
	v_mov_b32_e32 v83, v0
	v_mov_b32_e32 v84, v0
	v_mov_b32_e32 v85, v0
	v_mov_b32_e32 v86, v0
	v_mov_b32_e32 v87, v0
	v_mov_b32_e32 v88, v0
	v_mov_b32_e32 v89, v0
	v_mov_b32_e32 v90, v0
	v_mov_b32_e32 v91, v0
	v_mov_b32_e32 v92, v0
	v_mov_b32_e32 v93, v0
	v_mov_b32_e32 v94, v0
	v_mov_b32_e32 v95, v0
	v_add_u32_e32 v162, v131, v154
	v_add_u32_e32 v163, v131, v156
	v_add_u32_e32 v164, v131, v157
	v_add_u32_e32 v165, v131, v158
	v_add_u32_e32 v166, v153, v154
	v_add_u32_e32 v167, v153, v156
	v_add_u32_e32 v168, v153, v157
	v_add_u32_e32 v169, v153, v158
	v_add_u32_e32 v170, v155, v154
	v_add_u32_e32 v171, v155, v156
	v_add_u32_e32 v172, v155, v157
	v_add_u32_e32 v173, v155, v158
	v_lshl_add_u64 v[252:253], v[102:103], 0, v[98:99]
	v_lshl_add_u64 v[254:255], v[100:101], 0, v[98:99]
	v_readfirstlane_b32 s100, v121
	s_mov_b64 s[0:1], 0x80
	s_waitcnt vmcnt(0) lgkmcnt(0)
	s_barrier
	s_add_u32 m0, s100, 0x6000
	v_lshl_add_u64 v[106:107], v[252:253], 0, s[96:97]
	global_load_lds_dwordx4 v[106:107], off
	s_add_u32 m0, s100, 0x7000
	v_lshl_add_u64 v[106:107], v[252:253], 0, s[50:51]
	global_load_lds_dwordx4 v[106:107], off
	ds_read_b128 v[236:239], v166 offset:49152
	ds_read_b128 v[240:243], v166 offset:53248
	ds_read_b128 v[224:227], v162
	ds_read_b128 v[228:231], v162 offset:4096
	s_mov_b32 s101, 0
.Lgw_loop:
	ds_read_b128 v[232:235], v162 offset:8192
	s_waitcnt lgkmcnt(2)
	v_mfma_f32_32x32x16_bf16 v[80:95], v[224:227], v[236:239], v[80:95]
	v_mfma_f32_32x32x16_bf16 v[64:79], v[224:227], v[240:243], v[64:79]
	ds_read_b128 v[244:247], v167 offset:49152
	ds_read_b128 v[248:251], v167 offset:53248
	ds_read_b128 v[224:227], v163
	s_waitcnt lgkmcnt(4)
	v_mfma_f32_32x32x16_bf16 v[48:63], v[228:231], v[236:239], v[48:63]
	v_mfma_f32_32x32x16_bf16 v[32:47], v[228:231], v[240:243], v[32:47]
	s_add_u32 m0, s100, 0x8000
	v_lshl_add_u64 v[106:107], v[252:253], 0, s[24:25]
	global_load_lds_dwordx4 v[106:107], off
	s_add_u32 m0, s100, 0x9000
	v_lshl_add_u64 v[106:107], v[252:253], 0, s[26:27]
	global_load_lds_dwordx4 v[106:107], off
	ds_read_b128 v[228:231], v163 offset:4096
	s_waitcnt lgkmcnt(4)
	v_mfma_f32_32x32x16_bf16 v[16:31], v[232:235], v[236:239], v[16:31]
	v_mfma_f32_32x32x16_bf16 v[0:15], v[232:235], v[240:243], v[0:15]
	s_add_u32 m0, s100, 0xa000
	v_lshl_add_u64 v[106:107], v[252:253], 0, s[28:29]
	global_load_lds_dwordx4 v[106:107], off
	s_add_u32 m0, s100, 0xb000
	v_lshl_add_u64 v[106:107], v[252:253], 0, s[30:31]
	global_load_lds_dwordx4 v[106:107], off
	v_lshl_add_u64 v[252:253], v[252:253], 0, s[0:1]
	ds_read_b128 v[232:235], v163 offset:8192
	s_waitcnt lgkmcnt(2)
	v_mfma_f32_32x32x16_bf16 v[80:95], v[224:227], v[244:247], v[80:95]
	v_mfma_f32_32x32x16_bf16 v[64:79], v[224:227], v[248:251], v[64:79]
	s_mov_b64 s[16:17], 0x2100080
	s_add_u32 m0, s100, 0x10000
	v_lshl_add_u64 v[106:107], v[254:255], 0, s[16:17]
	global_load_lds_dwordx4 v[106:107], off
	s_mov_b64 s[16:17], 0x2110080
	s_add_u32 m0, s100, 0x11000
	v_lshl_add_u64 v[106:107], v[254:255], 0, s[16:17]
	global_load_lds_dwordx4 v[106:107], off
	ds_read_b128 v[236:239], v168 offset:49152
	ds_read_b128 v[240:243], v168 offset:53248
	ds_read_b128 v[224:227], v164
	s_waitcnt lgkmcnt(4)
	v_mfma_f32_32x32x16_bf16 v[48:63], v[228:231], v[244:247], v[48:63]
	v_mfma_f32_32x32x16_bf16 v[32:47], v[228:231], v[248:251], v[32:47]
	s_mov_b64 s[16:17], 0x2120080
	s_add_u32 m0, s100, 0x12000
	v_lshl_add_u64 v[106:107], v[254:255], 0, s[16:17]
	global_load_lds_dwordx4 v[106:107], off
	s_mov_b64 s[16:17], 0x2130080
	s_add_u32 m0, s100, 0x13000
	v_lshl_add_u64 v[106:107], v[254:255], 0, s[16:17]
	global_load_lds_dwordx4 v[106:107], off
	v_lshl_add_u64 v[254:255], v[254:255], 0, s[0:1]
	ds_read_b128 v[228:231], v164 offset:4096
	s_waitcnt lgkmcnt(4)
	v_mfma_f32_32x32x16_bf16 v[16:31], v[232:235], v[244:247], v[16:31]
	v_mfma_f32_32x32x16_bf16 v[0:15], v[232:235], v[248:251], v[0:15]
	ds_read_b128 v[232:235], v164 offset:8192
	s_waitcnt lgkmcnt(2)
	v_mfma_f32_32x32x16_bf16 v[80:95], v[224:227], v[236:239], v[80:95]
	v_mfma_f32_32x32x16_bf16 v[64:79], v[224:227], v[240:243], v[64:79]
	ds_read_b128 v[244:247], v169 offset:49152
	ds_read_b128 v[248:251], v169 offset:53248
	ds_read_b128 v[224:227], v165
	s_waitcnt lgkmcnt(4)
	v_mfma_f32_32x32x16_bf16 v[48:63], v[228:231], v[236:239], v[48:63]
	v_mfma_f32_32x32x16_bf16 v[32:47], v[228:231], v[240:243], v[32:47]
	ds_read_b128 v[228:231], v165 offset:4096
	s_waitcnt lgkmcnt(4)
	v_mfma_f32_32x32x16_bf16 v[16:31], v[232:235], v[236:239], v[16:31]
	v_mfma_f32_32x32x16_bf16 v[0:15], v[232:235], v[240:243], v[0:15]
	ds_read_b128 v[232:235], v165 offset:8192
	s_waitcnt lgkmcnt(2)
	v_mfma_f32_32x32x16_bf16 v[80:95], v[224:227], v[244:247], v[80:95]
	v_mfma_f32_32x32x16_bf16 v[64:79], v[224:227], v[248:251], v[64:79]
	s_waitcnt lgkmcnt(0)
	s_waitcnt vmcnt(0)
	s_barrier
	s_cmp_eq_u32 s101, 14
	s_cbranch_scc1 .Lgw_noearly
	s_mov_b32 m0, s100
	v_lshl_add_u64 v[106:107], v[252:253], 0, s[96:97]
	global_load_lds_dwordx4 v[106:107], off
	s_add_u32 m0, s100, 0x1000
	v_lshl_add_u64 v[106:107], v[252:253], 0, s[50:51]
	global_load_lds_dwordx4 v[106:107], off
; template <int EPI, int MI>
; DI void gemm_tile(const GemmDesc& g, int tm, int tn, char* smem) {
;     ...
;   const int rowA = wm * (32 * MI) + r, rowB = wn * 64 + r;
;   const int hk = hh ^ ((r & 7) ^ ((r >> 3) & 3));
;     ...
;   G_GLDS(0, 0);
;   asm volatile("s_waitcnt vmcnt(0)" ::: "memory");
;   __syncthreads();
;   for (int kt = 0; kt < nk; kt += 2) {
;     if (kt + 1 < nk) G_GLDS(kt + 1, 1);
;     G_COMPUTE(0);
;     asm volatile("s_waitcnt vmcnt(0)" ::: "memory");
;     __syncthreads();
;     if (kt + 1 < nk) {
;       if (kt + 2 < nk) G_GLDS(kt + 2, 0);
;       G_COMPUTE(1);
;       asm volatile("s_waitcnt vmcnt(0)" ::: "memory");
;       __syncthreads();
;     }
;   }
.Lgw_noearly:
	ds_read_b128 v[236:239], v170
	ds_read_b128 v[240:243], v170 offset:4096
	ds_read_b128 v[224:227], v162 offset:24576
	v_mfma_f32_32x32x16_bf16 v[48:63], v[228:231], v[244:247], v[48:63]
	v_mfma_f32_32x32x16_bf16 v[32:47], v[228:231], v[248:251], v[32:47]
	ds_read_b128 v[228:231], v162 offset:28672
	v_mfma_f32_32x32x16_bf16 v[16:31], v[232:235], v[244:247], v[16:31]
	v_mfma_f32_32x32x16_bf16 v[0:15], v[232:235], v[248:251], v[0:15]
	s_cmp_eq_u32 s101, 14
	s_cbranch_scc1 .Lgw_last
	ds_read_b128 v[232:235], v162 offset:32768
	s_waitcnt lgkmcnt(2)
	v_mfma_f32_32x32x16_bf16 v[80:95], v[224:227], v[236:239], v[80:95]
	v_mfma_f32_32x32x16_bf16 v[64:79], v[224:227], v[240:243], v[64:79]
	ds_read_b128 v[244:247], v171
	ds_read_b128 v[248:251], v171 offset:4096
	ds_read_b128 v[224:227], v163 offset:24576
	s_waitcnt lgkmcnt(4)
	v_mfma_f32_32x32x16_bf16 v[48:63], v[228:231], v[236:239], v[48:63]
	v_mfma_f32_32x32x16_bf16 v[32:47], v[228:231], v[240:243], v[32:47]
	s_add_u32 m0, s100, 0x2000
	v_lshl_add_u64 v[106:107], v[252:253], 0, s[24:25]
	global_load_lds_dwordx4 v[106:107], off
	s_add_u32 m0, s100, 0x3000
	v_lshl_add_u64 v[106:107], v[252:253], 0, s[26:27]
	global_load_lds_dwordx4 v[106:107], off
	ds_read_b128 v[228:231], v163 offset:28672
	s_waitcnt lgkmcnt(4)
	v_mfma_f32_32x32x16_bf16 v[16:31], v[232:235], v[236:239], v[16:31]
	v_mfma_f32_32x32x16_bf16 v[0:15], v[232:235], v[240:243], v[0:15]
	s_add_u32 m0, s100, 0x4000
	v_lshl_add_u64 v[106:107], v[252:253], 0, s[28:29]
	global_load_lds_dwordx4 v[106:107], off
	s_add_u32 m0, s100, 0x5000
	v_lshl_add_u64 v[106:107], v[252:253], 0, s[30:31]
	global_load_lds_dwordx4 v[106:107], off
	v_lshl_add_u64 v[252:253], v[252:253], 0, s[0:1]
	ds_read_b128 v[232:235], v163 offset:32768
	s_waitcnt lgkmcnt(2)
	v_mfma_f32_32x32x16_bf16 v[80:95], v[224:227], v[244:247], v[80:95]
	v_mfma_f32_32x32x16_bf16 v[64:79], v[224:227], v[248:251], v[64:79]
	s_mov_b64 s[16:17], 0x2100080
	s_add_u32 m0, s100, 0xc000
	v_lshl_add_u64 v[106:107], v[254:255], 0, s[16:17]
	global_load_lds_dwordx4 v[106:107], off
	s_mov_b64 s[16:17], 0x2110080
	s_add_u32 m0, s100, 0xd000
	v_lshl_add_u64 v[106:107], v[254:255], 0, s[16:17]
	global_load_lds_dwordx4 v[106:107], off
	ds_read_b128 v[236:239], v172
	ds_read_b128 v[240:243], v172 offset:4096
	ds_read_b128 v[224:227], v164 offset:24576
	s_waitcnt lgkmcnt(4)
	v_mfma_f32_32x32x16_bf16 v[48:63], v[228:231], v[244:247], v[48:63]
	v_mfma_f32_32x32x16_bf16 v[32:47], v[228:231], v[248:251], v[32:47]
	s_mov_b64 s[16:17], 0x2120080
	s_add_u32 m0, s100, 0xe000
	v_lshl_add_u64 v[106:107], v[254:255], 0, s[16:17]
	global_load_lds_dwordx4 v[106:107], off
	s_mov_b64 s[16:17], 0x2130080
	s_add_u32 m0, s100, 0xf000
	v_lshl_add_u64 v[106:107], v[254:255], 0, s[16:17]
	global_load_lds_dwordx4 v[106:107], off
	v_lshl_add_u64 v[254:255], v[254:255], 0, s[0:1]
	ds_read_b128 v[228:231], v164 offset:28672
	s_waitcnt lgkmcnt(4)
	v_mfma_f32_32x32x16_bf16 v[16:31], v[232:235], v[244:247], v[16:31]
	v_mfma_f32_32x32x16_bf16 v[0:15], v[232:235], v[248:251], v[0:15]
	ds_read_b128 v[232:235], v164 offset:32768
	s_waitcnt lgkmcnt(2)
	v_mfma_f32_32x32x16_bf16 v[80:95], v[224:227], v[236:239], v[80:95]
	v_mfma_f32_32x32x16_bf16 v[64:79], v[224:227], v[240:243], v[64:79]
	ds_read_b128 v[244:247], v173
	ds_read_b128 v[248:251], v173 offset:4096
	ds_read_b128 v[224:227], v165 offset:24576
	s_waitcnt lgkmcnt(4)
	v_mfma_f32_32x32x16_bf16 v[48:63], v[228:231], v[236:239], v[48:63]
	v_mfma_f32_32x32x16_bf16 v[32:47], v[228:231], v[240:243], v[32:47]
	ds_read_b128 v[228:231], v165 offset:28672
	s_waitcnt lgkmcnt(4)
	v_mfma_f32_32x32x16_bf16 v[16:31], v[232:235], v[236:239], v[16:31]
	v_mfma_f32_32x32x16_bf16 v[0:15], v[232:235], v[240:243], v[0:15]
	ds_read_b128 v[232:235], v165 offset:32768
	s_waitcnt lgkmcnt(2)
	v_mfma_f32_32x32x16_bf16 v[80:95], v[224:227], v[244:247], v[80:95]
	v_mfma_f32_32x32x16_bf16 v[64:79], v[224:227], v[248:251], v[64:79]
	s_waitcnt lgkmcnt(0)
	s_waitcnt vmcnt(0)
	s_barrier
	s_add_u32 m0, s100, 0x6000
	v_lshl_add_u64 v[106:107], v[252:253], 0, s[96:97]
	global_load_lds_dwordx4 v[106:107], off
	s_add_u32 m0, s100, 0x7000
	v_lshl_add_u64 v[106:107], v[252:253], 0, s[50:51]
	global_load_lds_dwordx4 v[106:107], off
	ds_read_b128 v[236:239], v166 offset:49152
	ds_read_b128 v[240:243], v166 offset:53248
	ds_read_b128 v[224:227], v162
	v_mfma_f32_32x32x16_bf16 v[48:63], v[228:231], v[244:247], v[48:63]
	v_mfma_f32_32x32x16_bf16 v[32:47], v[228:231], v[248:251], v[32:47]
	ds_read_b128 v[228:231], v162 offset:4096
	v_mfma_f32_32x32x16_bf16 v[16:31], v[232:235], v[244:247], v[16:31]
	v_mfma_f32_32x32x16_bf16 v[0:15], v[232:235], v[248:251], v[0:15]
	s_add_u32 s101, s101, 2
	s_branch .Lgw_loop

; template <int EPI, int MI>
; DI void gemm_tile(const GemmDesc& g, int tm, int tn, char* smem) {
;     ...
;   const int tid = get_tid(), lane = tid & 63, wave = tid >> 6, r = lane & 31, hh = lane >> 5;
;   const int wm = wave >> 1, wn = wave & 1;
;   const int m0 = tm * BM, n0 = tn * 128;
;   const int nk = g.K >> 6;
;   f32x16 acc[MI][2];
; #pragma unroll
;   for (int a = 0; a < MI; ++a)
; #pragma unroll
;     for (int b = 0; b < 2; ++b)
; #pragma unroll
;       for (int i = 0; i < 16; ++i) acc[a][b][i] = 0.f;
;   const int srow = tid >> 3;
;   const int schunk = (tid & 7) ^ ((srow & 7) ^ ((srow >> 3) & 3));
;     ...
;   const int rowA = wm * (32 * MI) + r, rowB = wn * 64 + r;
;   const int hk = hh ^ ((r & 7) ^ ((r >> 3) & 3));
;     ...
;   G_GLDS(0, 0);
;   asm volatile("s_waitcnt vmcnt(0)" ::: "memory");
;   __syncthreads();
;   for (int kt = 0; kt < nk; kt += 2) {
;     if (kt + 1 < nk) G_GLDS(kt + 1, 1);
; template <int EPI, int MI>
; DI void gemm_phase(const GemmDesc& g, char* smem, int vb, int nvb) {
;     ...
;     const int mg = q / per;
;     const int rem = q - mg * per;
;     const int tn = rem / PM;
;     const int tm = mbase + mg * PM + (rem - tn * PM);
.LBB0_1410:
	s_abs_i32 s1, s39
	s_mul_hi_u32 s40, s1, s17
	s_mul_i32 s41, s40, s15
	s_sub_i32 s1, s1, s41
	s_ashr_i32 s0, s39, 31
	s_add_i32 s41, s40, 1
	s_sub_i32 s42, s1, s15
	s_cmp_ge_u32 s1, s15
	s_cselect_b32 s40, s41, s40
	s_cselect_b32 s1, s42, s1
	s_add_i32 s41, s40, 1
	s_cmp_ge_u32 s1, s15
	s_cselect_b32 s1, s41, s40
	s_xor_b32 s1, s1, s0
	s_sub_i32 s40, s1, s0
	s_mul_i32 s41, s40, s15
	s_sub_i32 s42, s39, s41
	s_abs_i32 s41, s42
	s_mul_hi_u32 s44, s41, s18
	s_mul_i32 s45, s44, s4
	s_sub_i32 s41, s41, s45
	s_ashr_i32 s43, s42, 31
	s_add_i32 s45, s44, 1
	s_sub_i32 s46, s41, s4
	s_cmp_ge_u32 s41, s4
	s_cselect_b32 s44, s45, s44
	s_cselect_b32 s41, s46, s41
	s_add_i32 s45, s44, 1
	s_cmp_ge_u32 s41, s4
	s_cselect_b32 s41, s45, s44
	s_xor_b32 s44, s41, s43
	s_sub_i32 s41, s44, s43
	s_sub_i32 s40, s40, s41
	v_mov_b32_e32 v6, v132
	s_mul_i32 s40, s40, s4
	s_add_i32 s42, s42, s16
	s_add_i32 s42, s42, s40
	v_ashrrev_i32_e32 v76, 3, v6
	v_bfe_u32 v0, v6, 6, 2
	v_xor_b32_e32 v1, v76, v6
	s_lshl_b32 s40, s42, 7
	v_bitop3_b32 v2, v1, v0, 7 bitop3:0x6c
	v_ashrrev_i32_e32 v0, 1, v6
	v_and_b32_e32 v77, 7, v6
	v_and_b32_e32 v79, 0xffffffc0, v0
	v_lshrrev_b32_e32 v0, 3, v6
	v_add_u32_e32 v64, s40, v76
	v_bfe_u32 v78, v6, 5, 1
	v_bitop3_b32 v0, v0, v77, 3 bitop3:0x6c
	v_ashrrev_i32_e32 v65, 31, v64
	v_readlane_b32 s46, v223, 59
	v_and_b32_e32 v80, 31, v6
	v_bfe_u32 v81, v6, 6, 1
	v_xor_b32_e32 v9, v0, v78
	v_lshlrev_b64 v[0:1], 11, v[64:65]
	v_readlane_b32 s47, v223, 60
	v_lshlrev_b32_e32 v66, 4, v2
	v_lshl_add_u32 v2, s41, 7, v76
	v_lshlrev_b32_e32 v6, 4, v6
	v_lshl_add_u64 v[0:1], s[46:47], 0, v[0:1]
	v_ashrrev_i32_e32 v3, 31, v2
	v_readlane_b32 s46, v220, 54
	v_add_u32_e32 v65, 0, v6
	v_mov_b32_e32 v67, v96
	v_lshlrev_b64 v[2:3], 11, v[2:3]
	v_readlane_b32 s47, v220, 55
	v_readfirstlane_b32 s42, v65
	v_add_u32_e32 v82, 0x1000, v65
	v_lshl_add_u64 v[0:1], v[0:1], 0, v[66:67]
	v_lshl_add_u64 v[4:5], s[46:47], 0, v[2:3]
	s_mov_b32 m0, s42
	s_mov_b64 s[46:47], 0x10000
	v_readfirstlane_b32 s42, v82
	v_add_u32_e32 v83, 0x2000, v65
	global_load_lds_dwordx4 v[0:1], off
	v_lshl_add_u64 v[6:7], v[0:1], 0, s[46:47]
	s_mov_b32 m0, s42
	s_mov_b64 s[52:53], 0x20000
	v_readfirstlane_b32 s42, v83
	v_add_u32_e32 v84, 0x3000, v65
	global_load_lds_dwordx4 v[6:7], off
	v_lshl_add_u64 v[6:7], v[0:1], 0, s[52:53]
	s_mov_b32 m0, s42
	s_mov_b64 s[72:73], 0x30000
	v_readfirstlane_b32 s42, v84
	v_add_u32_e32 v85, 0x8000, v65
	global_load_lds_dwordx4 v[6:7], off
	v_lshl_add_u64 v[0:1], v[0:1], 0, s[72:73]
	s_mov_b32 m0, s42
	v_readfirstlane_b32 s42, v85
	v_add_u32_e32 v86, 0x9000, v65
	global_load_lds_dwordx4 v[0:1], off
	v_lshl_add_u64 v[0:1], v[4:5], 0, v[66:67]
	s_mov_b32 m0, s42
	v_readfirstlane_b32 s42, v86
	v_add_u32_e32 v87, 0xa000, v65
	global_load_lds_dwordx4 v[0:1], off
	v_lshl_add_u64 v[4:5], v[0:1], 0, s[46:47]
	s_mov_b32 m0, s42
	v_readfirstlane_b32 s42, v87
	v_add_u32_e32 v88, 0xb000, v65
	global_load_lds_dwordx4 v[4:5], off
	v_lshl_add_u64 v[4:5], v[0:1], 0, s[52:53]
	s_mov_b32 m0, s42
	v_readfirstlane_b32 s42, v88
	global_load_lds_dwordx4 v[4:5], off
	v_lshl_add_u64 v[0:1], v[0:1], 0, s[72:73]
	s_mov_b32 m0, s42
	s_mul_i32 s0, s0, 43
	global_load_lds_dwordx4 v[0:1], off
	s_add_i32 s43, s43, s0
	s_sub_i32 s0, s43, s44
	s_mul_i32 s1, s1, 43
	s_sub_i32 s0, s0, s1
	v_lshlrev_b32_e32 v0, 7, v80
	s_mul_i32 s0, s38, s0
	v_lshl_or_b32 v0, v81, 13, v0
	s_add_i32 s0, s0, s19
	v_add_u32_e32 v90, 0, v0
	v_add_u32_e32 v0, s0, v76
	v_ashrrev_i32_e32 v1, 31, v0
	s_waitcnt vmcnt(0)
	v_lshlrev_b64 v[0:1], 11, v[0:1]
	v_or_b32_e32 v8, v79, v80
	v_lshlrev_b32_e32 v91, 4, v9
	v_lshl_add_u64 v[68:69], s[70:71], 0, v[0:1]
	v_mov_b32_e32 v0, 0
	v_lshl_add_u32 v89, v8, 7, 0
	v_xor_b32_e32 v92, 32, v91
	v_xor_b32_e32 v93, 64, v91
	v_xor_b32_e32 v94, 0x60, v91
	v_lshl_add_u64 v[70:71], s[70:71], 0, v[2:3]
	s_mov_b32 s42, 0
	v_mov_b32_e32 v1, v0
	v_mov_b32_e32 v2, v0
	v_mov_b32_e32 v3, v0
	v_mov_b32_e32 v4, v0
	v_mov_b32_e32 v5, v0
	v_mov_b32_e32 v6, v0
	v_mov_b32_e32 v7, v0
	v_mov_b32_e32 v8, v0
	v_mov_b32_e32 v9, v0
	v_mov_b32_e32 v10, v0
	v_mov_b32_e32 v11, v0
	v_mov_b32_e32 v12, v0
	v_mov_b32_e32 v13, v0
	v_mov_b32_e32 v14, v0
	v_mov_b32_e32 v15, v0
	v_mov_b32_e32 v16, v0
	v_mov_b32_e32 v17, v0
	v_mov_b32_e32 v18, v0
	v_mov_b32_e32 v19, v0
	v_mov_b32_e32 v20, v0
	v_mov_b32_e32 v21, v0
	v_mov_b32_e32 v22, v0
	v_mov_b32_e32 v23, v0
	v_mov_b32_e32 v24, v0
	v_mov_b32_e32 v25, v0
	v_mov_b32_e32 v26, v0
	v_mov_b32_e32 v27, v0
	v_mov_b32_e32 v28, v0
	v_mov_b32_e32 v29, v0
	v_mov_b32_e32 v30, v0
	v_mov_b32_e32 v31, v0
	v_mov_b32_e32 v32, v0
	v_mov_b32_e32 v33, v0
	v_mov_b32_e32 v34, v0
	v_mov_b32_e32 v35, v0
	v_mov_b32_e32 v36, v0
	v_mov_b32_e32 v37, v0
	v_mov_b32_e32 v38, v0
	v_mov_b32_e32 v39, v0
	v_mov_b32_e32 v40, v0
	v_mov_b32_e32 v41, v0
	v_mov_b32_e32 v42, v0
	v_mov_b32_e32 v43, v0
	v_mov_b32_e32 v44, v0
	v_mov_b32_e32 v45, v0
	v_mov_b32_e32 v46, v0
	v_mov_b32_e32 v47, v0
	v_mov_b32_e32 v48, v0
	v_mov_b32_e32 v49, v0
	v_mov_b32_e32 v50, v0
	v_mov_b32_e32 v51, v0
	v_mov_b32_e32 v52, v0
	v_mov_b32_e32 v53, v0
	v_mov_b32_e32 v54, v0
	v_mov_b32_e32 v55, v0
	v_mov_b32_e32 v56, v0
	v_mov_b32_e32 v57, v0
	v_mov_b32_e32 v58, v0
	v_mov_b32_e32 v59, v0
	v_mov_b32_e32 v60, v0
	v_mov_b32_e32 v61, v0
	v_mov_b32_e32 v62, v0
	v_mov_b32_e32 v63, v0
	v_add_u32_e32 v98, v89, v91
	v_add_u32_e32 v99, v89, v92
	v_add_u32_e32 v100, v89, v93
	v_add_u32_e32 v101, v89, v94
	v_add_u32_e32 v102, v90, v91
	v_add_u32_e32 v103, v90, v92
	v_add_u32_e32 v104, v90, v93
	v_add_u32_e32 v105, v90, v94
	v_lshl_add_u64 v[72:73], v[68:69], 0, v[66:67]
	v_lshl_add_u64 v[74:75], v[70:71], 0, v[66:67]
	v_readfirstlane_b32 s100, v65
	s_mov_b64 s[44:45], 0x80
	s_waitcnt vmcnt(0) lgkmcnt(0)
	s_barrier
	s_add_u32 m0, s100, 0x4000
	v_lshl_add_u64 v[106:107], v[72:73], 0, s[96:97]
	global_load_lds_dwordx4 v[106:107], off
	s_add_u32 m0, s100, 0x5000
	v_lshl_add_u64 v[106:107], v[72:73], 0, s[50:51]
	global_load_lds_dwordx4 v[106:107], off
	ds_read_b128 v[240:243], v102 offset:32768
	ds_read_b128 v[244:247], v102 offset:36864
	ds_read_b128 v[224:227], v98
	ds_read_b128 v[228:231], v98 offset:4096
	s_mov_b32 s101, 0
; template <int EPI, int MI>
; DI void gemm_tile(const GemmDesc& g, int tm, int tn, char* smem) {
;     ...
;   const int rowA = wm * (32 * MI) + r, rowB = wn * 64 + r;
;   const int hk = hh ^ ((r & 7) ^ ((r >> 3) & 3));
;     ...
;   G_GLDS(0, 0);
;   asm volatile("s_waitcnt vmcnt(0)" ::: "memory");
;   __syncthreads();
;   for (int kt = 0; kt < nk; kt += 2) {
;     if (kt + 1 < nk) G_GLDS(kt + 1, 1);
;     G_COMPUTE(0);
;     asm volatile("s_waitcnt vmcnt(0)" ::: "memory");
;     __syncthreads();
;     if (kt + 1 < nk) {
;       if (kt + 2 < nk) G_GLDS(kt + 2, 0);
;       G_COMPUTE(1);
;       asm volatile("s_waitcnt vmcnt(0)" ::: "memory");
;       __syncthreads();
;     }
;   }
.Lgc_loop:
	ds_read_b128 v[248:251], v103 offset:32768
	ds_read_b128 v[252:255], v103 offset:36864
	ds_read_b128 v[232:235], v99
	s_waitcnt lgkmcnt(4)
	v_mfma_f32_32x32x16_bf16 v[48:63], v[224:227], v[240:243], v[48:63]
	v_mfma_f32_32x32x16_bf16 v[32:47], v[224:227], v[244:247], v[32:47]
	ds_read_b128 v[236:239], v99 offset:4096
	s_waitcnt lgkmcnt(4)
	v_mfma_f32_32x32x16_bf16 v[16:31], v[228:231], v[240:243], v[16:31]
	v_mfma_f32_32x32x16_bf16 v[0:15], v[228:231], v[244:247], v[0:15]
	s_add_u32 m0, s100, 0x6000
	v_lshl_add_u64 v[106:107], v[72:73], 0, s[24:25]
	global_load_lds_dwordx4 v[106:107], off
	s_add_u32 m0, s100, 0x7000
	v_lshl_add_u64 v[106:107], v[72:73], 0, s[26:27]
	global_load_lds_dwordx4 v[106:107], off
	v_lshl_add_u64 v[72:73], v[72:73], 0, s[44:45]
	ds_read_b128 v[240:243], v104 offset:32768
	ds_read_b128 v[244:247], v104 offset:36864
	ds_read_b128 v[224:227], v100
	s_waitcnt lgkmcnt(4)
	v_mfma_f32_32x32x16_bf16 v[48:63], v[232:235], v[248:251], v[48:63]
	v_mfma_f32_32x32x16_bf16 v[32:47], v[232:235], v[252:255], v[32:47]
	s_mov_b64 s[0:1], 0xb00080
	s_add_u32 m0, s100, 0xc000
	v_lshl_add_u64 v[106:107], v[74:75], 0, s[0:1]
	global_load_lds_dwordx4 v[106:107], off
	s_mov_b64 s[0:1], 0xb10080
	s_add_u32 m0, s100, 0xd000
	v_lshl_add_u64 v[106:107], v[74:75], 0, s[0:1]
	global_load_lds_dwordx4 v[106:107], off
	ds_read_b128 v[228:231], v100 offset:4096
	s_waitcnt lgkmcnt(4)
	v_mfma_f32_32x32x16_bf16 v[16:31], v[236:239], v[248:251], v[16:31]
	v_mfma_f32_32x32x16_bf16 v[0:15], v[236:239], v[252:255], v[0:15]
	s_mov_b64 s[0:1], 0xb20080
	s_add_u32 m0, s100, 0xe000
	v_lshl_add_u64 v[106:107], v[74:75], 0, s[0:1]
	global_load_lds_dwordx4 v[106:107], off
	s_mov_b64 s[0:1], 0xb30080
	s_add_u32 m0, s100, 0xf000
	v_lshl_add_u64 v[106:107], v[74:75], 0, s[0:1]
	global_load_lds_dwordx4 v[106:107], off
	v_lshl_add_u64 v[74:75], v[74:75], 0, s[44:45]
	ds_read_b128 v[248:251], v105 offset:32768
	ds_read_b128 v[252:255], v105 offset:36864
	ds_read_b128 v[232:235], v101
	s_waitcnt lgkmcnt(4)
	v_mfma_f32_32x32x16_bf16 v[48:63], v[224:227], v[240:243], v[48:63]
	v_mfma_f32_32x32x16_bf16 v[32:47], v[224:227], v[244:247], v[32:47]
	ds_read_b128 v[236:239], v101 offset:4096
	s_waitcnt lgkmcnt(4)
	v_mfma_f32_32x32x16_bf16 v[16:31], v[228:231], v[240:243], v[16:31]
	v_mfma_f32_32x32x16_bf16 v[0:15], v[228:231], v[244:247], v[0:15]
	s_waitcnt lgkmcnt(0)
	s_waitcnt vmcnt(0)
	s_barrier
	s_cmp_eq_u32 s101, 14
	s_cbranch_scc1 .Lgc_noearly
	s_mov_b32 m0, s100
	v_lshl_add_u64 v[106:107], v[72:73], 0, s[96:97]
	global_load_lds_dwordx4 v[106:107], off
	s_add_u32 m0, s100, 0x1000
	v_lshl_add_u64 v[106:107], v[72:73], 0, s[50:51]
	global_load_lds_dwordx4 v[106:107], off
.Lgc_noearly:
	ds_read_b128 v[240:243], v102 offset:49152
	ds_read_b128 v[244:247], v102 offset:53248
	ds_read_b128 v[224:227], v98 offset:16384
	v_mfma_f32_32x32x16_bf16 v[48:63], v[232:235], v[248:251], v[48:63]
	v_mfma_f32_32x32x16_bf16 v[32:47], v[232:235], v[252:255], v[32:47]
	ds_read_b128 v[228:231], v98 offset:20480
	v_mfma_f32_32x32x16_bf16 v[16:31], v[236:239], v[248:251], v[16:31]
	v_mfma_f32_32x32x16_bf16 v[0:15], v[236:239], v[252:255], v[0:15]
	s_cmp_eq_u32 s101, 14
	s_cbranch_scc1 .Lgc_last
	ds_read_b128 v[248:251], v103 offset:49152
	ds_read_b128 v[252:255], v103 offset:53248
	ds_read_b128 v[232:235], v99 offset:16384
	s_waitcnt lgkmcnt(4)
	v_mfma_f32_32x32x16_bf16 v[48:63], v[224:227], v[240:243], v[48:63]
	v_mfma_f32_32x32x16_bf16 v[32:47], v[224:227], v[244:247], v[32:47]
	ds_read_b128 v[236:239], v99 offset:20480
	s_waitcnt lgkmcnt(4)
	v_mfma_f32_32x32x16_bf16 v[16:31], v[228:231], v[240:243], v[16:31]
	v_mfma_f32_32x32x16_bf16 v[0:15], v[228:231], v[244:247], v[0:15]
	s_add_u32 m0, s100, 0x2000
	v_lshl_add_u64 v[106:107], v[72:73], 0, s[24:25]
	global_load_lds_dwordx4 v[106:107], off
	s_add_u32 m0, s100, 0x3000
	v_lshl_add_u64 v[106:107], v[72:73], 0, s[26:27]
	global_load_lds_dwordx4 v[106:107], off
	v_lshl_add_u64 v[72:73], v[72:73], 0, s[44:45]
	ds_read_b128 v[240:243], v104 offset:49152
	ds_read_b128 v[244:247], v104 offset:53248
	ds_read_b128 v[224:227], v100 offset:16384
	s_waitcnt lgkmcnt(4)
	v_mfma_f32_32x32x16_bf16 v[48:63], v[232:235], v[248:251], v[48:63]
	v_mfma_f32_32x32x16_bf16 v[32:47], v[232:235], v[252:255], v[32:47]
	s_mov_b64 s[0:1], 0xb00080
	s_add_u32 m0, s100, 0x8000
	v_lshl_add_u64 v[106:107], v[74:75], 0, s[0:1]
	global_load_lds_dwordx4 v[106:107], off
	s_mov_b64 s[0:1], 0xb10080
	s_add_u32 m0, s100, 0x9000
	v_lshl_add_u64 v[106:107], v[74:75], 0, s[0:1]
	global_load_lds_dwordx4 v[106:107], off
	ds_read_b128 v[228:231], v100 offset:20480
	s_waitcnt lgkmcnt(4)
	v_mfma_f32_32x32x16_bf16 v[16:31], v[236:239], v[248:251], v[16:31]
	v_mfma_f32_32x32x16_bf16 v[0:15], v[236:239], v[252:255], v[0:15]
	s_mov_b64 s[0:1], 0xb20080
	s_add_u32 m0, s100, 0xa000
	v_lshl_add_u64 v[106:107], v[74:75], 0, s[0:1]
	global_load_lds_dwordx4 v[106:107], off
	s_mov_b64 s[0:1], 0xb30080
	s_add_u32 m0, s100, 0xb000
	v_lshl_add_u64 v[106:107], v[74:75], 0, s[0:1]
	global_load_lds_dwordx4 v[106:107], off
	v_lshl_add_u64 v[74:75], v[74:75], 0, s[44:45]
	ds_read_b128 v[248:251], v105 offset:49152
	ds_read_b128 v[252:255], v105 offset:53248
	ds_read_b128 v[232:235], v101 offset:16384
	s_waitcnt lgkmcnt(4)
	v_mfma_f32_32x32x16_bf16 v[48:63], v[224:227], v[240:243], v[48:63]
	v_mfma_f32_32x32x16_bf16 v[32:47], v[224:227], v[244:247], v[32:47]
	ds_read_b128 v[236:239], v101 offset:20480
	s_waitcnt lgkmcnt(4)
	v_mfma_f32_32x32x16_bf16 v[16:31], v[228:231], v[240:243], v[16:31]
	v_mfma_f32_32x32x16_bf16 v[0:15], v[228:231], v[244:247], v[0:15]
	s_waitcnt lgkmcnt(0)
	s_waitcnt vmcnt(0)
	s_barrier
	s_add_u32 m0, s100, 0x4000
	v_lshl_add_u64 v[106:107], v[72:73], 0, s[96:97]
	global_load_lds_dwordx4 v[106:107], off
	s_add_u32 m0, s100, 0x5000
	v_lshl_add_u64 v[106:107], v[72:73], 0, s[50:51]
	global_load_lds_dwordx4 v[106:107], off
	ds_read_b128 v[240:243], v102 offset:32768
	ds_read_b128 v[244:247], v102 offset:36864
	ds_read_b128 v[224:227], v98
	v_mfma_f32_32x32x16_bf16 v[48:63], v[232:235], v[248:251], v[48:63]
	v_mfma_f32_32x32x16_bf16 v[32:47], v[232:235], v[252:255], v[32:47]
	ds_read_b128 v[228:231], v98 offset:4096
	v_mfma_f32_32x32x16_bf16 v[16:31], v[236:239], v[248:251], v[16:31]
	v_mfma_f32_32x32x16_bf16 v[0:15], v[236:239], v[252:255], v[0:15]
	s_add_u32 s101, s101, 2
	s_branch .Lgc_loop

; template <int EPI, int MI>
; DI void gemm_tile(const GemmDesc& g, int tm, int tn, char* smem) {
;     ...
;   const int srow = tid >> 3;
;   const int schunk = (tid & 7) ^ ((srow & 7) ^ ((srow >> 3) & 3));
; template <int EPI, int MI>
; DI void gemm_phase(const GemmDesc& g, char* smem, int vb, int nvb) {
;     ...
;     const int mg = q / per;
;     const int rem = q - mg * per;
;     const int tn = rem / PM;
;     const int tm = mbase + mg * PM + (rem - tn * PM);
.LBB0_1421:
	s_abs_i32 s1, s5
	v_readlane_b32 s15, v219, 45
	s_mul_hi_u32 s15, s1, s15
	v_readlane_b32 s18, v219, 44
	s_mul_i32 s16, s15, s18
	s_sub_i32 s1, s1, s16
	s_ashr_i32 s0, s5, 31
	s_add_i32 s16, s15, 1
	s_sub_i32 s17, s1, s18
	s_cmp_ge_u32 s1, s18
	s_cselect_b32 s15, s16, s15
	s_cselect_b32 s1, s17, s1
	s_add_i32 s16, s15, 1
	s_cmp_ge_u32 s1, s18
	s_cselect_b32 s1, s16, s15
	s_xor_b32 s1, s1, s0
	s_sub_i32 s15, s1, s0
	s_mul_i32 s16, s15, s18
	s_sub_i32 s16, s5, s16
	s_abs_i32 s18, s16
	v_readlane_b32 s19, v219, 46
	s_mul_hi_u32 s19, s18, s19
	v_readlane_b32 s40, v218, 32
	s_mul_i32 s38, s19, s40
	s_sub_i32 s18, s18, s38
	s_ashr_i32 s17, s16, 31
	s_add_i32 s38, s19, 1
	s_sub_i32 s39, s18, s40
	s_cmp_ge_u32 s18, s40
	s_cselect_b32 s19, s38, s19
	s_cselect_b32 s18, s39, s18
	s_add_i32 s38, s19, 1
	s_cmp_ge_u32 s18, s40
	s_cselect_b32 s18, s38, s19
	s_xor_b32 s18, s18, s17
	s_sub_i32 s39, s18, s17
	s_sub_i32 s15, s15, s39
	v_mov_b32_e32 v6, v132
	s_mul_i32 s15, s15, s40
	s_add_i32 s16, s16, s54
	s_add_i32 s38, s16, s15
	v_ashrrev_i32_e32 v97, 3, v6
	v_ashrrev_i32_e32 v120, 7, v6
	v_bfe_u32 v0, v6, 6, 2
	v_xor_b32_e32 v1, v97, v6
	s_mulk_i32 s38, 0xc0
	v_and_b32_e32 v121, 31, v6
	v_bitop3_b32 v2, v1, v0, 7 bitop3:0x6c
	v_mul_lo_u32 v0, v120, s6
	v_and_b32_e32 v115, 7, v6
	v_or_b32_e32 v8, v0, v121
	v_lshrrev_b32_e32 v0, 3, v6
	s_waitcnt vmcnt(10)
	v_add_u32_e32 v98, s38, v97
	v_bfe_u32 v122, v6, 5, 1
	v_bitop3_b32 v0, v0, v115, 3 bitop3:0x6c
	v_ashrrev_i32_e32 v99, 31, v98
	v_readlane_b32 s40, v223, 59
	v_xor_b32_e32 v9, v0, v122
	v_lshlrev_b64 v[0:1], 11, v[98:99]
	v_readlane_b32 s41, v223, 60
	v_lshlrev_b32_e32 v100, 4, v2
	v_lshl_add_u32 v2, s39, 7, v97
	v_lshlrev_b32_e32 v99, 4, v6
	v_lshl_add_u64 v[0:1], s[40:41], 0, v[0:1]
	v_ashrrev_i32_e32 v3, 31, v2
	v_readlane_b32 s40, v220, 54
	v_add_u32_e32 v124, 0, v99
	v_mov_b32_e32 v101, v96
	v_lshlrev_b64 v[2:3], 11, v[2:3]
	v_readlane_b32 s41, v220, 55
	v_readfirstlane_b32 s15, v124
	v_add_u32_e32 v125, 0x1000, v124
	v_lshl_add_u64 v[0:1], v[0:1], 0, v[100:101]
	v_lshl_add_u64 v[4:5], s[40:41], 0, v[2:3]
	s_mov_b32 m0, s15
	s_mov_b64 s[40:41], 0x10000
	v_readfirstlane_b32 s15, v125
	v_add_u32_e32 v126, 0x2000, v124
	v_bfe_u32 v123, v6, 6, 1
	global_load_lds_dwordx4 v[0:1], off
	v_lshl_add_u64 v[6:7], v[0:1], 0, s[40:41]
	s_mov_b32 m0, s15
	s_mov_b64 s[42:43], 0x20000
	v_readfirstlane_b32 s15, v126
	v_add_u32_e32 v127, 0x3000, v124
	global_load_lds_dwordx4 v[6:7], off
	v_lshl_add_u64 v[6:7], v[0:1], 0, s[42:43]
	s_mov_b32 m0, s15
	s_mov_b64 s[44:45], 0x30000
	v_readfirstlane_b32 s15, v127
	v_add_u32_e32 v128, 0x4000, v124
	global_load_lds_dwordx4 v[6:7], off
	v_lshl_add_u64 v[6:7], v[0:1], 0, s[44:45]
	s_mov_b32 m0, s15
	s_mov_b64 s[46:47], 0x40000
	v_readfirstlane_b32 s15, v128
	v_add_u32_e32 v129, 0x5000, v124
	global_load_lds_dwordx4 v[6:7], off
	v_lshl_add_u64 v[6:7], v[0:1], 0, s[46:47]
	s_mov_b32 m0, s15
	s_mov_b64 s[46:47], 0x50000
	v_readfirstlane_b32 s15, v129
	v_add_u32_e32 v130, 0xc000, v124
	global_load_lds_dwordx4 v[6:7], off
	v_lshl_add_u64 v[0:1], v[0:1], 0, s[46:47]
	s_mov_b32 m0, s15
	v_readfirstlane_b32 s15, v130
	v_add_u32_e32 v131, 0xd000, v124
	global_load_lds_dwordx4 v[0:1], off
	v_lshl_add_u64 v[0:1], v[4:5], 0, v[100:101]
	s_mov_b32 m0, s15
	v_readfirstlane_b32 s15, v131
	v_add_u32_e32 v153, 0xe000, v124
	global_load_lds_dwordx4 v[0:1], off
	v_lshl_add_u64 v[4:5], v[0:1], 0, s[40:41]
	s_mov_b32 m0, s15
	v_readfirstlane_b32 s15, v153
	v_add_u32_e32 v154, 0xf000, v124
	global_load_lds_dwordx4 v[4:5], off
	v_lshl_add_u64 v[4:5], v[0:1], 0, s[42:43]
	s_mov_b32 m0, s15
	v_readfirstlane_b32 s15, v154
	global_load_lds_dwordx4 v[4:5], off
	v_lshl_add_u64 v[0:1], v[0:1], 0, s[44:45]
	s_mov_b32 m0, s15
	s_mul_i32 s0, s0, 43
	global_load_lds_dwordx4 v[0:1], off
	s_add_i32 s17, s17, s0
	s_sub_i32 s0, s17, s18
	s_mul_i32 s1, s1, 43
	s_sub_i32 s0, s0, s1
	v_readlane_b32 s1, v218, 33
	v_lshlrev_b32_e32 v0, 7, v121
	s_mul_i32 s0, s1, s0
	v_lshl_or_b32 v0, v123, 13, v0
	s_add_i32 s0, s0, s4
	v_add_u32_e32 v156, 0, v0
	v_add_u32_e32 v158, s10, v0
	v_add_u32_e32 v0, s0, v97
	v_ashrrev_i32_e32 v1, 31, v0
	s_waitcnt vmcnt(0)
	v_lshlrev_b64 v[0:1], 11, v[0:1]
	v_lshlrev_b32_e32 v157, 4, v9
	s_waitcnt vmcnt(0)
; template <int EPI, int MI>
; DI void gemm_tile(const GemmDesc& g, int tm, int tn, char* smem) {
;     ...
;   f32x16 acc[MI][2];
; #pragma unroll
;   for (int a = 0; a < MI; ++a)
; #pragma unroll
;     for (int b = 0; b < 2; ++b)
; #pragma unroll
;       for (int i = 0; i < 16; ++i) acc[a][b][i] = 0.f;
;   const int srow = tid >> 3;
;   const int schunk = (tid & 7) ^ ((srow & 7) ^ ((srow >> 3) & 3));
;     ...
;   const int rowA = wm * (32 * MI) + r, rowB = wn * 64 + r;
;   const int hk = hh ^ ((r & 7) ^ ((r >> 3) & 3));
;     ...
;   G_GLDS(0, 0);
;   asm volatile("s_waitcnt vmcnt(0)" ::: "memory");
;   __syncthreads();
;   for (int kt = 0; kt < nk; kt += 2) {
;     if (kt + 1 < nk) G_GLDS(kt + 1, 1);
	v_lshl_add_u64 v[102:103], s[70:71], 0, v[0:1]
	v_mov_b32_e32 v0, 0
	v_lshl_add_u32 v155, v8, 7, 0
	v_xor_b32_e32 v159, 32, v157
	v_xor_b32_e32 v160, 64, v157
	v_xor_b32_e32 v161, 0x60, v157
	v_lshl_add_u64 v[104:105], s[70:71], 0, v[2:3]
	s_mov_b32 s15, 0
	v_mov_b32_e32 v1, v0
	v_mov_b32_e32 v2, v0
	v_mov_b32_e32 v3, v0
	v_mov_b32_e32 v4, v0
	v_mov_b32_e32 v5, v0
	v_mov_b32_e32 v6, v0
	v_mov_b32_e32 v7, v0
	v_mov_b32_e32 v8, v0
	v_mov_b32_e32 v9, v0
	v_mov_b32_e32 v10, v0
	v_mov_b32_e32 v11, v0
	v_mov_b32_e32 v12, v0
	v_mov_b32_e32 v13, v0
	v_mov_b32_e32 v14, v0
	v_mov_b32_e32 v15, v0
	v_mov_b32_e32 v16, v0
	v_mov_b32_e32 v17, v0
	v_mov_b32_e32 v18, v0
	v_mov_b32_e32 v19, v0
	v_mov_b32_e32 v20, v0
	v_mov_b32_e32 v21, v0
	v_mov_b32_e32 v22, v0
	v_mov_b32_e32 v23, v0
	v_mov_b32_e32 v24, v0
	v_mov_b32_e32 v25, v0
	v_mov_b32_e32 v26, v0
	v_mov_b32_e32 v27, v0
	v_mov_b32_e32 v28, v0
	v_mov_b32_e32 v29, v0
	v_mov_b32_e32 v30, v0
	v_mov_b32_e32 v31, v0
	v_mov_b32_e32 v32, v0
	v_mov_b32_e32 v33, v0
	v_mov_b32_e32 v34, v0
	v_mov_b32_e32 v35, v0
	v_mov_b32_e32 v36, v0
	v_mov_b32_e32 v37, v0
	v_mov_b32_e32 v38, v0
	v_mov_b32_e32 v39, v0
	v_mov_b32_e32 v40, v0
	v_mov_b32_e32 v41, v0
	v_mov_b32_e32 v42, v0
	v_mov_b32_e32 v43, v0
	v_mov_b32_e32 v44, v0
	v_mov_b32_e32 v45, v0
	v_mov_b32_e32 v46, v0
	v_mov_b32_e32 v47, v0
	v_mov_b32_e32 v48, v0
	v_mov_b32_e32 v49, v0
	v_mov_b32_e32 v50, v0
	v_mov_b32_e32 v51, v0
	v_mov_b32_e32 v52, v0
	v_mov_b32_e32 v53, v0
	v_mov_b32_e32 v54, v0
	v_mov_b32_e32 v55, v0
	v_mov_b32_e32 v56, v0
	v_mov_b32_e32 v57, v0
	v_mov_b32_e32 v58, v0
	v_mov_b32_e32 v59, v0
	v_mov_b32_e32 v60, v0
	v_mov_b32_e32 v61, v0
	v_mov_b32_e32 v62, v0
	v_mov_b32_e32 v63, v0
	v_mov_b32_e32 v64, v0
	v_mov_b32_e32 v65, v0
	v_mov_b32_e32 v66, v0
	v_mov_b32_e32 v67, v0
	v_mov_b32_e32 v68, v0
	v_mov_b32_e32 v69, v0
	v_mov_b32_e32 v70, v0
	v_mov_b32_e32 v71, v0
	v_mov_b32_e32 v72, v0
	v_mov_b32_e32 v73, v0
	v_mov_b32_e32 v74, v0
	v_mov_b32_e32 v75, v0
	v_mov_b32_e32 v76, v0
	v_mov_b32_e32 v77, v0
	v_mov_b32_e32 v78, v0
	v_mov_b32_e32 v79, v0
	v_mov_b32_e32 v80, v0
	v_mov_b32_e32 v81, v0
	v_mov_b32_e32 v82, v0
	v_mov_b32_e32 v83, v0
	v_mov_b32_e32 v84, v0
	v_mov_b32_e32 v85, v0
	v_mov_b32_e32 v86, v0
	v_mov_b32_e32 v87, v0
	v_mov_b32_e32 v88, v0
	v_mov_b32_e32 v89, v0
	v_mov_b32_e32 v90, v0
	v_mov_b32_e32 v91, v0
	v_mov_b32_e32 v92, v0
	v_mov_b32_e32 v93, v0
	v_mov_b32_e32 v94, v0
	v_mov_b32_e32 v95, v0
	v_add_u32_e32 v162, v155, v157
	v_add_u32_e32 v163, v155, v159
	v_add_u32_e32 v164, v155, v160
	v_add_u32_e32 v165, v155, v161
	v_add_u32_e32 v166, v156, v157
	v_add_u32_e32 v167, v156, v159
	v_add_u32_e32 v168, v156, v160
	v_add_u32_e32 v169, v156, v161
	v_add_u32_e32 v170, v158, v157
	v_add_u32_e32 v171, v158, v159
	v_add_u32_e32 v172, v158, v160
	v_add_u32_e32 v173, v158, v161
	v_lshl_add_u64 v[252:253], v[102:103], 0, v[100:101]
	v_lshl_add_u64 v[254:255], v[104:105], 0, v[100:101]
	v_readfirstlane_b32 s100, v124
	s_mov_b64 s[0:1], 0x80
	s_waitcnt vmcnt(0) lgkmcnt(0)
	s_barrier
	s_add_u32 m0, s100, 0x6000
	v_lshl_add_u64 v[106:107], v[252:253], 0, s[96:97]
	global_load_lds_dwordx4 v[106:107], off
	s_add_u32 m0, s100, 0x7000
	v_lshl_add_u64 v[106:107], v[252:253], 0, s[50:51]
	global_load_lds_dwordx4 v[106:107], off
	ds_read_b128 v[236:239], v166 offset:49152
	ds_read_b128 v[240:243], v166 offset:53248
	ds_read_b128 v[224:227], v162
	ds_read_b128 v[228:231], v162 offset:4096
	s_mov_b32 s101, 0
.Lgb_loop:
	ds_read_b128 v[232:235], v162 offset:8192
	s_waitcnt lgkmcnt(2)
	v_mfma_f32_32x32x16_bf16 v[80:95], v[224:227], v[236:239], v[80:95]
	v_mfma_f32_32x32x16_bf16 v[64:79], v[224:227], v[240:243], v[64:79]
	ds_read_b128 v[244:247], v167 offset:49152
	ds_read_b128 v[248:251], v167 offset:53248
	ds_read_b128 v[224:227], v163
	s_waitcnt lgkmcnt(4)
	v_mfma_f32_32x32x16_bf16 v[48:63], v[228:231], v[236:239], v[48:63]
	v_mfma_f32_32x32x16_bf16 v[32:47], v[228:231], v[240:243], v[32:47]
	s_add_u32 m0, s100, 0x8000
	v_lshl_add_u64 v[106:107], v[252:253], 0, s[24:25]
	global_load_lds_dwordx4 v[106:107], off
	s_add_u32 m0, s100, 0x9000
	v_lshl_add_u64 v[106:107], v[252:253], 0, s[26:27]
	global_load_lds_dwordx4 v[106:107], off
	ds_read_b128 v[228:231], v163 offset:4096
	s_waitcnt lgkmcnt(4)
	v_mfma_f32_32x32x16_bf16 v[16:31], v[232:235], v[236:239], v[16:31]
	v_mfma_f32_32x32x16_bf16 v[0:15], v[232:235], v[240:243], v[0:15]
	s_add_u32 m0, s100, 0xa000
	v_lshl_add_u64 v[106:107], v[252:253], 0, s[28:29]
	global_load_lds_dwordx4 v[106:107], off
	s_add_u32 m0, s100, 0xb000
	v_lshl_add_u64 v[106:107], v[252:253], 0, s[30:31]
	global_load_lds_dwordx4 v[106:107], off
	v_lshl_add_u64 v[252:253], v[252:253], 0, s[0:1]
	ds_read_b128 v[232:235], v163 offset:8192
	s_waitcnt lgkmcnt(2)
	v_mfma_f32_32x32x16_bf16 v[80:95], v[224:227], v[244:247], v[80:95]
	v_mfma_f32_32x32x16_bf16 v[64:79], v[224:227], v[248:251], v[64:79]
	s_mov_b64 s[16:17], 0xb00080
	s_add_u32 m0, s100, 0x10000
	v_lshl_add_u64 v[106:107], v[254:255], 0, s[16:17]
	global_load_lds_dwordx4 v[106:107], off
	s_mov_b64 s[16:17], 0xb10080
	s_add_u32 m0, s100, 0x11000
	v_lshl_add_u64 v[106:107], v[254:255], 0, s[16:17]
	global_load_lds_dwordx4 v[106:107], off
	ds_read_b128 v[236:239], v168 offset:49152
	ds_read_b128 v[240:243], v168 offset:53248
	ds_read_b128 v[224:227], v164
	s_waitcnt lgkmcnt(4)
	v_mfma_f32_32x32x16_bf16 v[48:63], v[228:231], v[244:247], v[48:63]
	v_mfma_f32_32x32x16_bf16 v[32:47], v[228:231], v[248:251], v[32:47]
	s_mov_b64 s[16:17], 0xb20080
	s_add_u32 m0, s100, 0x12000
	v_lshl_add_u64 v[106:107], v[254:255], 0, s[16:17]
	global_load_lds_dwordx4 v[106:107], off
	s_mov_b64 s[16:17], 0xb30080
	s_add_u32 m0, s100, 0x13000
	v_lshl_add_u64 v[106:107], v[254:255], 0, s[16:17]
	global_load_lds_dwordx4 v[106:107], off
	v_lshl_add_u64 v[254:255], v[254:255], 0, s[0:1]
	ds_read_b128 v[228:231], v164 offset:4096
	s_waitcnt lgkmcnt(4)
	v_mfma_f32_32x32x16_bf16 v[16:31], v[232:235], v[244:247], v[16:31]
	v_mfma_f32_32x32x16_bf16 v[0:15], v[232:235], v[248:251], v[0:15]
	ds_read_b128 v[232:235], v164 offset:8192
	s_waitcnt lgkmcnt(2)
	v_mfma_f32_32x32x16_bf16 v[80:95], v[224:227], v[236:239], v[80:95]
	v_mfma_f32_32x32x16_bf16 v[64:79], v[224:227], v[240:243], v[64:79]
	ds_read_b128 v[244:247], v169 offset:49152
	ds_read_b128 v[248:251], v169 offset:53248
	ds_read_b128 v[224:227], v165
	s_waitcnt lgkmcnt(4)
	v_mfma_f32_32x32x16_bf16 v[48:63], v[228:231], v[236:239], v[48:63]
	v_mfma_f32_32x32x16_bf16 v[32:47], v[228:231], v[240:243], v[32:47]
	ds_read_b128 v[228:231], v165 offset:4096
	s_waitcnt lgkmcnt(4)
	v_mfma_f32_32x32x16_bf16 v[16:31], v[232:235], v[236:239], v[16:31]
	v_mfma_f32_32x32x16_bf16 v[0:15], v[232:235], v[240:243], v[0:15]
	ds_read_b128 v[232:235], v165 offset:8192
	s_waitcnt lgkmcnt(2)
	v_mfma_f32_32x32x16_bf16 v[80:95], v[224:227], v[244:247], v[80:95]
	v_mfma_f32_32x32x16_bf16 v[64:79], v[224:227], v[248:251], v[64:79]
	s_waitcnt lgkmcnt(0)
	s_waitcnt vmcnt(0)
	s_barrier
; template <int EPI, int MI>
; DI void gemm_tile(const GemmDesc& g, int tm, int tn, char* smem) {
;     ...
;   const int rowA = wm * (32 * MI) + r, rowB = wn * 64 + r;
;   const int hk = hh ^ ((r & 7) ^ ((r >> 3) & 3));
;     ...
;   G_GLDS(0, 0);
;   asm volatile("s_waitcnt vmcnt(0)" ::: "memory");
;   __syncthreads();
;   for (int kt = 0; kt < nk; kt += 2) {
;     if (kt + 1 < nk) G_GLDS(kt + 1, 1);
;     G_COMPUTE(0);
;     asm volatile("s_waitcnt vmcnt(0)" ::: "memory");
;     __syncthreads();
;     if (kt + 1 < nk) {
;       if (kt + 2 < nk) G_GLDS(kt + 2, 0);
;       G_COMPUTE(1);
;       asm volatile("s_waitcnt vmcnt(0)" ::: "memory");
;       __syncthreads();
;     }
;   }
	s_cmp_eq_u32 s101, 14
	s_cbranch_scc1 .Lgb_noearly
	s_mov_b32 m0, s100
	v_lshl_add_u64 v[106:107], v[252:253], 0, s[96:97]
	global_load_lds_dwordx4 v[106:107], off
	s_add_u32 m0, s100, 0x1000
	v_lshl_add_u64 v[106:107], v[252:253], 0, s[50:51]
	global_load_lds_dwordx4 v[106:107], off
.Lgb_noearly:
	ds_read_b128 v[236:239], v170
	ds_read_b128 v[240:243], v170 offset:4096
	ds_read_b128 v[224:227], v162 offset:24576
	v_mfma_f32_32x32x16_bf16 v[48:63], v[228:231], v[244:247], v[48:63]
	v_mfma_f32_32x32x16_bf16 v[32:47], v[228:231], v[248:251], v[32:47]
	ds_read_b128 v[228:231], v162 offset:28672
	v_mfma_f32_32x32x16_bf16 v[16:31], v[232:235], v[244:247], v[16:31]
	v_mfma_f32_32x32x16_bf16 v[0:15], v[232:235], v[248:251], v[0:15]
	s_cmp_eq_u32 s101, 14
	s_cbranch_scc1 .Lgb_last
	ds_read_b128 v[232:235], v162 offset:32768
	s_waitcnt lgkmcnt(2)
	v_mfma_f32_32x32x16_bf16 v[80:95], v[224:227], v[236:239], v[80:95]
	v_mfma_f32_32x32x16_bf16 v[64:79], v[224:227], v[240:243], v[64:79]
	ds_read_b128 v[244:247], v171
	ds_read_b128 v[248:251], v171 offset:4096
	ds_read_b128 v[224:227], v163 offset:24576
	s_waitcnt lgkmcnt(4)
	v_mfma_f32_32x32x16_bf16 v[48:63], v[228:231], v[236:239], v[48:63]
	v_mfma_f32_32x32x16_bf16 v[32:47], v[228:231], v[240:243], v[32:47]
	s_add_u32 m0, s100, 0x2000
	v_lshl_add_u64 v[106:107], v[252:253], 0, s[24:25]
	global_load_lds_dwordx4 v[106:107], off
	s_add_u32 m0, s100, 0x3000
	v_lshl_add_u64 v[106:107], v[252:253], 0, s[26:27]
	global_load_lds_dwordx4 v[106:107], off
	ds_read_b128 v[228:231], v163 offset:28672
	s_waitcnt lgkmcnt(4)
	v_mfma_f32_32x32x16_bf16 v[16:31], v[232:235], v[236:239], v[16:31]
	v_mfma_f32_32x32x16_bf16 v[0:15], v[232:235], v[240:243], v[0:15]
	s_add_u32 m0, s100, 0x4000
	v_lshl_add_u64 v[106:107], v[252:253], 0, s[28:29]
	global_load_lds_dwordx4 v[106:107], off
	s_add_u32 m0, s100, 0x5000
	v_lshl_add_u64 v[106:107], v[252:253], 0, s[30:31]
	global_load_lds_dwordx4 v[106:107], off
	v_lshl_add_u64 v[252:253], v[252:253], 0, s[0:1]
	ds_read_b128 v[232:235], v163 offset:32768
	s_waitcnt lgkmcnt(2)
	v_mfma_f32_32x32x16_bf16 v[80:95], v[224:227], v[244:247], v[80:95]
	v_mfma_f32_32x32x16_bf16 v[64:79], v[224:227], v[248:251], v[64:79]
	s_mov_b64 s[16:17], 0xb00080
	s_add_u32 m0, s100, 0xc000
	v_lshl_add_u64 v[106:107], v[254:255], 0, s[16:17]
	global_load_lds_dwordx4 v[106:107], off
	s_mov_b64 s[16:17], 0xb10080
	s_add_u32 m0, s100, 0xd000
	v_lshl_add_u64 v[106:107], v[254:255], 0, s[16:17]
	global_load_lds_dwordx4 v[106:107], off
	ds_read_b128 v[236:239], v172
	ds_read_b128 v[240:243], v172 offset:4096
	ds_read_b128 v[224:227], v164 offset:24576
	s_waitcnt lgkmcnt(4)
	v_mfma_f32_32x32x16_bf16 v[48:63], v[228:231], v[244:247], v[48:63]
	v_mfma_f32_32x32x16_bf16 v[32:47], v[228:231], v[248:251], v[32:47]
	s_mov_b64 s[16:17], 0xb20080
	s_add_u32 m0, s100, 0xe000
	v_lshl_add_u64 v[106:107], v[254:255], 0, s[16:17]
	global_load_lds_dwordx4 v[106:107], off
	s_mov_b64 s[16:17], 0xb30080
	s_add_u32 m0, s100, 0xf000
	v_lshl_add_u64 v[106:107], v[254:255], 0, s[16:17]
	global_load_lds_dwordx4 v[106:107], off
	v_lshl_add_u64 v[254:255], v[254:255], 0, s[0:1]
	ds_read_b128 v[228:231], v164 offset:28672
	s_waitcnt lgkmcnt(4)
	v_mfma_f32_32x32x16_bf16 v[16:31], v[232:235], v[244:247], v[16:31]
	v_mfma_f32_32x32x16_bf16 v[0:15], v[232:235], v[248:251], v[0:15]
	ds_read_b128 v[232:235], v164 offset:32768
	s_waitcnt lgkmcnt(2)
	v_mfma_f32_32x32x16_bf16 v[80:95], v[224:227], v[236:239], v[80:95]
	v_mfma_f32_32x32x16_bf16 v[64:79], v[224:227], v[240:243], v[64:79]
	ds_read_b128 v[244:247], v173
	ds_read_b128 v[248:251], v173 offset:4096
	ds_read_b128 v[224:227], v165 offset:24576
	s_waitcnt lgkmcnt(4)
	v_mfma_f32_32x32x16_bf16 v[48:63], v[228:231], v[236:239], v[48:63]
	v_mfma_f32_32x32x16_bf16 v[32:47], v[228:231], v[240:243], v[32:47]
	ds_read_b128 v[228:231], v165 offset:28672
	s_waitcnt lgkmcnt(4)
	v_mfma_f32_32x32x16_bf16 v[16:31], v[232:235], v[236:239], v[16:31]
	v_mfma_f32_32x32x16_bf16 v[0:15], v[232:235], v[240:243], v[0:15]
	ds_read_b128 v[232:235], v165 offset:32768
	s_waitcnt lgkmcnt(2)
	v_mfma_f32_32x32x16_bf16 v[80:95], v[224:227], v[244:247], v[80:95]
	v_mfma_f32_32x32x16_bf16 v[64:79], v[224:227], v[248:251], v[64:79]
	s_waitcnt lgkmcnt(0)
	s_waitcnt vmcnt(0)
	s_barrier
	s_add_u32 m0, s100, 0x6000
	v_lshl_add_u64 v[106:107], v[252:253], 0, s[96:97]
	global_load_lds_dwordx4 v[106:107], off
	s_add_u32 m0, s100, 0x7000
	v_lshl_add_u64 v[106:107], v[252:253], 0, s[50:51]
	global_load_lds_dwordx4 v[106:107], off
	ds_read_b128 v[236:239], v166 offset:49152
	ds_read_b128 v[240:243], v166 offset:53248
	ds_read_b128 v[224:227], v162
	v_mfma_f32_32x32x16_bf16 v[48:63], v[228:231], v[244:247], v[48:63]
	v_mfma_f32_32x32x16_bf16 v[32:47], v[228:231], v[248:251], v[32:47]
	ds_read_b128 v[228:231], v162 offset:4096
	v_mfma_f32_32x32x16_bf16 v[16:31], v[232:235], v[244:247], v[16:31]
	v_mfma_f32_32x32x16_bf16 v[0:15], v[232:235], v[248:251], v[0:15]
	s_add_u32 s101, s101, 2
	s_branch .Lgb_loop

; template <int EPI, int MI>
; DI void gemm_tile(const GemmDesc& g, int tm, int tn, char* smem) {
;     ...
;   const int tid = get_tid(), lane = tid & 63, wave = tid >> 6, r = lane & 31, hh = lane >> 5;
;   const int wm = wave >> 1, wn = wave & 1;
;   const int m0 = tm * BM, n0 = tn * 128;
;   const int nk = g.K >> 6;
;   f32x16 acc[MI][2];
; #pragma unroll
;   for (int a = 0; a < MI; ++a)
; #pragma unroll
;     for (int b = 0; b < 2; ++b)
; #pragma unroll
;       for (int i = 0; i < 16; ++i) acc[a][b][i] = 0.f;
;   const int srow = tid >> 3;
;   const int schunk = (tid & 7) ^ ((srow & 7) ^ ((srow >> 3) & 3));
;     ...
;   const int rowA = wm * (32 * MI) + r, rowB = wn * 64 + r;
;   const int hk = hh ^ ((r & 7) ^ ((r >> 3) & 3));
;     ...
;   G_GLDS(0, 0);
;   asm volatile("s_waitcnt vmcnt(0)" ::: "memory");
;   __syncthreads();
;   for (int kt = 0; kt < nk; kt += 2) {
;     if (kt + 1 < nk) G_GLDS(kt + 1, 1);
; template <int EPI, int MI>
; DI void gemm_phase(const GemmDesc& g, char* smem, int vb, int nvb) {
;     ...
;     const int mg = q / per;
;     const int rem = q - mg * per;
;     const int tn = rem / PM;
;     const int tm = mbase + mg * PM + (rem - tn * PM);
.LBB0_1478:
	s_abs_i32 s0, s44
	s_mul_hi_u32 s1, s0, s42
	s_mul_i32 s4, s1, s38
	s_sub_i32 s0, s0, s4
	s_ashr_i32 s18, s44, 31
	s_add_i32 s4, s1, 1
	s_sub_i32 s5, s0, s38
	s_cmp_ge_u32 s0, s38
	s_cselect_b32 s1, s4, s1
	s_cselect_b32 s0, s5, s0
	s_add_i32 s4, s1, 1
	s_cmp_ge_u32 s0, s38
	s_cselect_b32 s0, s4, s1
	s_xor_b32 s19, s0, s18
	s_sub_i32 s0, s19, s18
	s_mul_i32 s1, s0, s38
	s_sub_i32 s1, s44, s1
	s_abs_i32 s4, s1
	s_mul_hi_u32 s5, s4, s16
	s_mul_i32 s45, s5, s15
	s_sub_i32 s4, s4, s45
	s_ashr_i32 s46, s1, 31
	s_add_i32 s45, s5, 1
	s_sub_i32 s47, s4, s15
	s_cmp_ge_u32 s4, s15
	s_cselect_b32 s5, s45, s5
	s_cselect_b32 s4, s47, s4
	s_add_i32 s45, s5, 1
	s_cmp_ge_u32 s4, s15
	s_cselect_b32 s4, s45, s5
	s_xor_b32 s47, s4, s46
	s_sub_i32 s4, s47, s46
	v_mov_b32_e32 v75, v132
	s_mul_i32 s0, s0, s15
	s_mul_i32 s5, s4, s15
	s_add_i32 s0, s0, s39
	v_ashrrev_i32_e32 v6, 3, v75
	s_sub_i32 s1, s1, s5
	v_bfe_u32 v1, v75, 6, 2
	v_xor_b32_e32 v2, v6, v75
	s_add_i32 s1, s0, s1
	s_lshl_b32 s0, s4, 7
	v_and_b32_e32 v0, 7, v75
	v_bitop3_b32 v2, v2, v1, 7 bitop3:0x6c
	v_lshrrev_b32_e32 v1, 3, v75
	v_readlane_b32 s4, v221, 5
	s_lshl_b32 s45, s1, 7
	v_bfe_u32 v77, v75, 5, 1
	v_bitop3_b32 v0, v1, v0, 3 bitop3:0x6c
	v_readlane_b32 s5, v221, 6
	v_xor_b32_e32 v7, v0, v77
	v_add_u32_e32 v3, s45, v6
	v_mov_b64_e32 v[0:1], s[4:5]
	s_movk_i32 s52, 0x1600
	v_mad_i64_i32 v[0:1], s[4:5], v3, s52, v[0:1]
	v_readlane_b32 s4, v220, 56
	v_readlane_b32 s5, v220, 57
	v_lshlrev_b32_e32 v64, 4, v2
	v_add_u32_e32 v8, s0, v6
	v_mov_b64_e32 v[2:3], s[4:5]
	v_lshlrev_b32_e32 v4, 4, v75
	v_mad_i64_i32 v[2:3], s[4:5], v8, s52, v[2:3]
	v_add_u32_e32 v78, 0, v4
	v_mov_b32_e32 v65, v96
	v_readfirstlane_b32 s4, v78
	v_add_u32_e32 v79, 0x1000, v78
	v_lshl_add_u64 v[0:1], v[0:1], 0, v[64:65]
	s_mov_b32 m0, s4
	s_mov_b64 s[72:73], 0x2c000
	v_readfirstlane_b32 s4, v79
	v_add_u32_e32 v80, 0x2000, v78
	global_load_lds_dwordx4 v[0:1], off
	v_lshl_add_u64 v[4:5], v[0:1], 0, s[72:73]
	s_mov_b32 m0, s4
	s_mov_b64 s[74:75], 0x58000
	v_readfirstlane_b32 s4, v80
	v_add_u32_e32 v81, 0x3000, v78
	global_load_lds_dwordx4 v[4:5], off
	v_lshl_add_u64 v[4:5], v[0:1], 0, s[74:75]
	s_mov_b32 m0, s4
	s_mov_b64 s[76:77], 0x84000
	v_readfirstlane_b32 s4, v81
	v_add_u32_e32 v82, 0x8000, v78
	global_load_lds_dwordx4 v[4:5], off
	v_lshl_add_u64 v[0:1], v[0:1], 0, s[76:77]
	s_mov_b32 m0, s4
	v_readfirstlane_b32 s4, v82
	v_add_u32_e32 v83, 0x9000, v78
	global_load_lds_dwordx4 v[0:1], off
	v_lshl_add_u64 v[0:1], v[2:3], 0, v[64:65]
	s_mov_b32 m0, s4
	v_readfirstlane_b32 s4, v83
	v_add_u32_e32 v84, 0xa000, v78
	global_load_lds_dwordx4 v[0:1], off
	v_lshl_add_u64 v[2:3], v[0:1], 0, s[72:73]
	s_mov_b32 m0, s4
	v_readfirstlane_b32 s4, v84
	v_add_u32_e32 v85, 0xb000, v78
	global_load_lds_dwordx4 v[2:3], off
	v_lshl_add_u64 v[2:3], v[0:1], 0, s[74:75]
	s_mov_b32 m0, s4
	v_readfirstlane_b32 s4, v85
	global_load_lds_dwordx4 v[2:3], off
	v_lshl_add_u64 v[0:1], v[0:1], 0, s[76:77]
	s_mov_b32 m0, s4
	s_mul_i32 s18, s18, 7
	global_load_lds_dwordx4 v[0:1], off
	v_and_b32_e32 v74, 31, v75
	s_add_i32 s46, s46, s18
	v_ashrrev_i32_e32 v76, 7, v75
	v_lshlrev_b32_e32 v0, 7, v74
	s_sub_i32 s4, s46, s47
	s_mul_i32 s19, s19, 7
	v_lshl_or_b32 v0, v76, 13, v0
	s_sub_i32 s4, s4, s19
	v_add_u32_e32 v86, 0, v0
	v_lshlrev_b32_e32 v0, 7, v75
	s_mul_i32 s4, s43, s4
	v_and_b32_e32 v0, 0x2f80, v0
	s_add_i32 s4, s4, s17
	s_waitcnt vmcnt(0)
	v_add_u32_e32 v87, 0, v0
	v_add_u32_e32 v2, s4, v6
	v_mov_b64_e32 v[0:1], s[70:71]
	s_waitcnt vmcnt(0)
	v_lshlrev_b32_e32 v88, 4, v7
	v_mad_i64_i32 v[66:67], s[4:5], v2, s52, v[0:1]
	v_mad_i64_i32 v[68:69], s[4:5], v8, s52, v[0:1]
	v_mov_b32_e32 v0, 0
	v_xor_b32_e32 v89, 32, v88
	v_xor_b32_e32 v90, 64, v88
	v_xor_b32_e32 v91, 0x60, v88
	s_mov_b32 s18, 0
	v_mov_b32_e32 v1, v0
	v_mov_b32_e32 v2, v0
	v_mov_b32_e32 v3, v0
	v_mov_b32_e32 v4, v0
	v_mov_b32_e32 v5, v0
	v_mov_b32_e32 v6, v0
	v_mov_b32_e32 v7, v0
	v_mov_b32_e32 v8, v0
	v_mov_b32_e32 v9, v0
	v_mov_b32_e32 v10, v0
	v_mov_b32_e32 v11, v0
	v_mov_b32_e32 v12, v0
	v_mov_b32_e32 v13, v0
	v_mov_b32_e32 v14, v0
	v_mov_b32_e32 v15, v0
	v_mov_b32_e32 v16, v0
	v_mov_b32_e32 v17, v0
	v_mov_b32_e32 v18, v0
	v_mov_b32_e32 v19, v0
	v_mov_b32_e32 v20, v0
	v_mov_b32_e32 v21, v0
	v_mov_b32_e32 v22, v0
	v_mov_b32_e32 v23, v0
	v_mov_b32_e32 v24, v0
	v_mov_b32_e32 v25, v0
	v_mov_b32_e32 v26, v0
	v_mov_b32_e32 v27, v0
	v_mov_b32_e32 v28, v0
	v_mov_b32_e32 v29, v0
	v_mov_b32_e32 v30, v0
	v_mov_b32_e32 v31, v0
	v_mov_b32_e32 v32, v0
	v_mov_b32_e32 v33, v0
	v_mov_b32_e32 v34, v0
	v_mov_b32_e32 v35, v0
	v_mov_b32_e32 v36, v0
	v_mov_b32_e32 v37, v0
	v_mov_b32_e32 v38, v0
	v_mov_b32_e32 v39, v0
	v_mov_b32_e32 v40, v0
	v_mov_b32_e32 v41, v0
	v_mov_b32_e32 v42, v0
	v_mov_b32_e32 v43, v0
	v_mov_b32_e32 v44, v0
	v_mov_b32_e32 v45, v0
	v_mov_b32_e32 v46, v0
	v_mov_b32_e32 v47, v0
	v_mov_b32_e32 v48, v0
	v_mov_b32_e32 v49, v0
	v_mov_b32_e32 v50, v0
	v_mov_b32_e32 v51, v0
	v_mov_b32_e32 v52, v0
	v_mov_b32_e32 v53, v0
	v_mov_b32_e32 v54, v0
	v_mov_b32_e32 v55, v0
	v_mov_b32_e32 v56, v0
	v_mov_b32_e32 v57, v0
	v_mov_b32_e32 v58, v0
	v_mov_b32_e32 v59, v0
	v_mov_b32_e32 v60, v0
	v_mov_b32_e32 v61, v0
	v_mov_b32_e32 v62, v0
	v_mov_b32_e32 v63, v0
	v_add_u32_e32 v92, v86, v88
	v_add_u32_e32 v93, v86, v89
	v_add_u32_e32 v94, v86, v90
	v_add_u32_e32 v95, v86, v91
	v_add_u32_e32 v97, v87, v88
	v_add_u32_e32 v98, v87, v89
	v_add_u32_e32 v99, v87, v90
	v_add_u32_e32 v100, v87, v91
	v_lshl_add_u64 v[104:105], v[66:67], 0, v[64:65]
	v_lshl_add_u64 v[106:107], v[68:69], 0, v[64:65]
	v_readfirstlane_b32 s100, v78
	s_mov_b64 s[46:47], 0x80
	s_waitcnt vmcnt(0) lgkmcnt(0)
	s_barrier
	s_mov_b64 s[4:5], 0x5872080
	s_add_u32 m0, s100, 0x4000
	v_lshl_add_u64 v[102:103], v[104:105], 0, s[4:5]
	global_load_lds_dwordx4 v[102:103], off
	s_mov_b64 s[4:5], 0x589e080
	s_add_u32 m0, s100, 0x5000
	v_lshl_add_u64 v[102:103], v[104:105], 0, s[4:5]
	global_load_lds_dwordx4 v[102:103], off
	ds_read_b128 v[240:243], v97 offset:32768
	ds_read_b128 v[244:247], v97 offset:36864
	ds_read_b128 v[224:227], v92
	ds_read_b128 v[228:231], v92 offset:4096
	s_mov_b32 s101, 0
; template <int EPI, int MI>
; DI void gemm_tile(const GemmDesc& g, int tm, int tn, char* smem) {
;     ...
;   const int rowA = wm * (32 * MI) + r, rowB = wn * 64 + r;
;   const int hk = hh ^ ((r & 7) ^ ((r >> 3) & 3));
;     ...
;   G_GLDS(0, 0);
;   asm volatile("s_waitcnt vmcnt(0)" ::: "memory");
;   __syncthreads();
;   for (int kt = 0; kt < nk; kt += 2) {
;     if (kt + 1 < nk) G_GLDS(kt + 1, 1);
;     G_COMPUTE(0);
;     asm volatile("s_waitcnt vmcnt(0)" ::: "memory");
;     __syncthreads();
;     if (kt + 1 < nk) {
;       if (kt + 2 < nk) G_GLDS(kt + 2, 0);
;       G_COMPUTE(1);
;       asm volatile("s_waitcnt vmcnt(0)" ::: "memory");
;       __syncthreads();
;     }
;   }
.Lgf_loop:
	ds_read_b128 v[248:251], v98 offset:32768
	ds_read_b128 v[252:255], v98 offset:36864
	ds_read_b128 v[232:235], v93
	s_waitcnt lgkmcnt(4)
	v_mfma_f32_32x32x16_bf16 v[48:63], v[224:227], v[240:243], v[48:63]
	v_mfma_f32_32x32x16_bf16 v[32:47], v[224:227], v[244:247], v[32:47]
	ds_read_b128 v[236:239], v93 offset:4096
	s_waitcnt lgkmcnt(4)
	v_mfma_f32_32x32x16_bf16 v[16:31], v[228:231], v[240:243], v[16:31]
	v_mfma_f32_32x32x16_bf16 v[0:15], v[228:231], v[244:247], v[0:15]
	s_mov_b64 s[4:5], 0x58ca080
	s_add_u32 m0, s100, 0x6000
	v_lshl_add_u64 v[102:103], v[104:105], 0, s[4:5]
	global_load_lds_dwordx4 v[102:103], off
	s_mov_b64 s[4:5], 0x58f6080
	s_add_u32 m0, s100, 0x7000
	v_lshl_add_u64 v[102:103], v[104:105], 0, s[4:5]
	global_load_lds_dwordx4 v[102:103], off
	v_lshl_add_u64 v[104:105], v[104:105], 0, s[46:47]
	ds_read_b128 v[240:243], v99 offset:32768
	ds_read_b128 v[244:247], v99 offset:36864
	ds_read_b128 v[224:227], v94
	s_waitcnt lgkmcnt(4)
	v_mfma_f32_32x32x16_bf16 v[48:63], v[232:235], v[248:251], v[48:63]
	v_mfma_f32_32x32x16_bf16 v[32:47], v[232:235], v[252:255], v[32:47]
	s_mov_b64 s[4:5], 0x1b80080
	s_add_u32 m0, s100, 0xc000
	v_lshl_add_u64 v[102:103], v[106:107], 0, s[4:5]
	global_load_lds_dwordx4 v[102:103], off
	s_mov_b64 s[4:5], 0x1bac080
	s_add_u32 m0, s100, 0xd000
	v_lshl_add_u64 v[102:103], v[106:107], 0, s[4:5]
	global_load_lds_dwordx4 v[102:103], off
	ds_read_b128 v[228:231], v94 offset:4096
	s_waitcnt lgkmcnt(4)
	v_mfma_f32_32x32x16_bf16 v[16:31], v[236:239], v[248:251], v[16:31]
	v_mfma_f32_32x32x16_bf16 v[0:15], v[236:239], v[252:255], v[0:15]
	s_mov_b64 s[4:5], 0x1bd8080
	s_add_u32 m0, s100, 0xe000
	v_lshl_add_u64 v[102:103], v[106:107], 0, s[4:5]
	global_load_lds_dwordx4 v[102:103], off
	s_mov_b64 s[4:5], 0x1c04080
	s_add_u32 m0, s100, 0xf000
	v_lshl_add_u64 v[102:103], v[106:107], 0, s[4:5]
	global_load_lds_dwordx4 v[102:103], off
	v_lshl_add_u64 v[106:107], v[106:107], 0, s[46:47]
	ds_read_b128 v[248:251], v100 offset:32768
	ds_read_b128 v[252:255], v100 offset:36864
	ds_read_b128 v[232:235], v95
	s_waitcnt lgkmcnt(4)
	v_mfma_f32_32x32x16_bf16 v[48:63], v[224:227], v[240:243], v[48:63]
	v_mfma_f32_32x32x16_bf16 v[32:47], v[224:227], v[244:247], v[32:47]
	ds_read_b128 v[236:239], v95 offset:4096
	s_waitcnt lgkmcnt(4)
	v_mfma_f32_32x32x16_bf16 v[16:31], v[228:231], v[240:243], v[16:31]
	v_mfma_f32_32x32x16_bf16 v[0:15], v[228:231], v[244:247], v[0:15]
	s_waitcnt lgkmcnt(0)
	s_waitcnt vmcnt(0)
	s_barrier
	s_cmp_eq_u32 s101, 42
	s_cbranch_scc1 .Lgf_noearly
	s_mov_b64 s[4:5], 0x5872080
	s_mov_b32 m0, s100
	v_lshl_add_u64 v[102:103], v[104:105], 0, s[4:5]
	global_load_lds_dwordx4 v[102:103], off
	s_mov_b64 s[4:5], 0x589e080
	s_add_u32 m0, s100, 0x1000
	v_lshl_add_u64 v[102:103], v[104:105], 0, s[4:5]
	global_load_lds_dwordx4 v[102:103], off
.Lgf_noearly:
	ds_read_b128 v[240:243], v97 offset:49152
	ds_read_b128 v[244:247], v97 offset:53248
	ds_read_b128 v[224:227], v92 offset:16384
	v_mfma_f32_32x32x16_bf16 v[48:63], v[232:235], v[248:251], v[48:63]
	v_mfma_f32_32x32x16_bf16 v[32:47], v[232:235], v[252:255], v[32:47]
	ds_read_b128 v[228:231], v92 offset:20480
	v_mfma_f32_32x32x16_bf16 v[16:31], v[236:239], v[248:251], v[16:31]
	v_mfma_f32_32x32x16_bf16 v[0:15], v[236:239], v[252:255], v[0:15]
	s_cmp_eq_u32 s101, 42
	s_cbranch_scc1 .Lgf_last
	ds_read_b128 v[248:251], v98 offset:49152
	ds_read_b128 v[252:255], v98 offset:53248
	ds_read_b128 v[232:235], v93 offset:16384
	s_waitcnt lgkmcnt(4)
	v_mfma_f32_32x32x16_bf16 v[48:63], v[224:227], v[240:243], v[48:63]
	v_mfma_f32_32x32x16_bf16 v[32:47], v[224:227], v[244:247], v[32:47]
	ds_read_b128 v[236:239], v93 offset:20480
	s_waitcnt lgkmcnt(4)
	v_mfma_f32_32x32x16_bf16 v[16:31], v[228:231], v[240:243], v[16:31]
	v_mfma_f32_32x32x16_bf16 v[0:15], v[228:231], v[244:247], v[0:15]
	s_mov_b64 s[4:5], 0x58ca080
	s_add_u32 m0, s100, 0x2000
	v_lshl_add_u64 v[102:103], v[104:105], 0, s[4:5]
	global_load_lds_dwordx4 v[102:103], off
	s_mov_b64 s[4:5], 0x58f6080
	s_add_u32 m0, s100, 0x3000
	v_lshl_add_u64 v[102:103], v[104:105], 0, s[4:5]
	global_load_lds_dwordx4 v[102:103], off
	v_lshl_add_u64 v[104:105], v[104:105], 0, s[46:47]
	ds_read_b128 v[240:243], v99 offset:49152
	ds_read_b128 v[244:247], v99 offset:53248
	ds_read_b128 v[224:227], v94 offset:16384
	s_waitcnt lgkmcnt(4)
	v_mfma_f32_32x32x16_bf16 v[48:63], v[232:235], v[248:251], v[48:63]
	v_mfma_f32_32x32x16_bf16 v[32:47], v[232:235], v[252:255], v[32:47]
	s_mov_b64 s[4:5], 0x1b80080
	s_add_u32 m0, s100, 0x8000
	v_lshl_add_u64 v[102:103], v[106:107], 0, s[4:5]
	global_load_lds_dwordx4 v[102:103], off
	s_mov_b64 s[4:5], 0x1bac080
	s_add_u32 m0, s100, 0x9000
	v_lshl_add_u64 v[102:103], v[106:107], 0, s[4:5]
	global_load_lds_dwordx4 v[102:103], off
	ds_read_b128 v[228:231], v94 offset:20480
	s_waitcnt lgkmcnt(4)
	v_mfma_f32_32x32x16_bf16 v[16:31], v[236:239], v[248:251], v[16:31]
	v_mfma_f32_32x32x16_bf16 v[0:15], v[236:239], v[252:255], v[0:15]
	s_mov_b64 s[4:5], 0x1bd8080
	s_add_u32 m0, s100, 0xa000
	v_lshl_add_u64 v[102:103], v[106:107], 0, s[4:5]
	global_load_lds_dwordx4 v[102:103], off
	s_mov_b64 s[4:5], 0x1c04080
	s_add_u32 m0, s100, 0xb000
	v_lshl_add_u64 v[102:103], v[106:107], 0, s[4:5]
	global_load_lds_dwordx4 v[102:103], off
	v_lshl_add_u64 v[106:107], v[106:107], 0, s[46:47]
	ds_read_b128 v[248:251], v100 offset:49152
	ds_read_b128 v[252:255], v100 offset:53248
	ds_read_b128 v[232:235], v95 offset:16384
	s_waitcnt lgkmcnt(4)
	v_mfma_f32_32x32x16_bf16 v[48:63], v[224:227], v[240:243], v[48:63]
	v_mfma_f32_32x32x16_bf16 v[32:47], v[224:227], v[244:247], v[32:47]
	ds_read_b128 v[236:239], v95 offset:20480
	s_waitcnt lgkmcnt(4)
	v_mfma_f32_32x32x16_bf16 v[16:31], v[228:231], v[240:243], v[16:31]
	v_mfma_f32_32x32x16_bf16 v[0:15], v[228:231], v[244:247], v[0:15]
	s_waitcnt lgkmcnt(0)
	s_waitcnt vmcnt(0)
	s_barrier
	s_mov_b64 s[4:5], 0x5872080
	s_add_u32 m0, s100, 0x4000
	v_lshl_add_u64 v[102:103], v[104:105], 0, s[4:5]
	global_load_lds_dwordx4 v[102:103], off
	s_mov_b64 s[4:5], 0x589e080
	s_add_u32 m0, s100, 0x5000
	v_lshl_add_u64 v[102:103], v[104:105], 0, s[4:5]
	global_load_lds_dwordx4 v[102:103], off
	ds_read_b128 v[240:243], v97 offset:32768
	ds_read_b128 v[244:247], v97 offset:36864
	ds_read_b128 v[224:227], v92
	v_mfma_f32_32x32x16_bf16 v[48:63], v[232:235], v[248:251], v[48:63]
	v_mfma_f32_32x32x16_bf16 v[32:47], v[232:235], v[252:255], v[32:47]
	ds_read_b128 v[228:231], v92 offset:4096
	v_mfma_f32_32x32x16_bf16 v[16:31], v[236:239], v[248:251], v[16:31]
	v_mfma_f32_32x32x16_bf16 v[0:15], v[236:239], v[252:255], v[0:15]
	s_add_u32 s101, s101, 2
	s_branch .Lgf_loop

; template <int EPI, int MI>
; DI void gemm_tile(const GemmDesc& g, int tm, int tn, char* smem) {
;     ...
;   const int srow = tid >> 3;
;   const int schunk = (tid & 7) ^ ((srow & 7) ^ ((srow >> 3) & 3));
; template <int EPI, int MI>
; DI void gemm_phase(const GemmDesc& g, char* smem, int vb, int nvb) {
;     ...
;     const int mg = q / per;
;     const int rem = q - mg * per;
;     const int tn = rem / PM;
;     const int tm = mbase + mg * PM + (rem - tn * PM);
.LBB0_1491:
	s_abs_i32 s0, s40
	v_readlane_b32 s1, v219, 48
	s_mul_hi_u32 s1, s0, s1
	v_readlane_b32 s17, v219, 47
	s_mul_i32 s4, s1, s17
	s_sub_i32 s0, s0, s4
	s_ashr_i32 s15, s40, 31
	s_add_i32 s4, s1, 1
	s_sub_i32 s5, s0, s17
	s_cmp_ge_u32 s0, s17
	s_cselect_b32 s1, s4, s1
	s_cselect_b32 s0, s5, s0
	s_add_i32 s4, s1, 1
	s_cmp_ge_u32 s0, s17
	s_cselect_b32 s0, s4, s1
	s_xor_b32 s16, s0, s15
	s_sub_i32 s0, s16, s15
	s_mul_i32 s1, s0, s17
	s_sub_i32 s1, s40, s1
	s_abs_i32 s4, s1
	v_readlane_b32 s5, v219, 46
	s_mul_hi_u32 s5, s4, s5
	v_readlane_b32 s41, v218, 32
	s_mul_i32 s18, s5, s41
	s_sub_i32 s4, s4, s18
	s_ashr_i32 s17, s1, 31
	s_add_i32 s18, s5, 1
	s_sub_i32 s19, s4, s41
	s_cmp_ge_u32 s4, s41
	s_cselect_b32 s5, s18, s5
	s_cselect_b32 s4, s19, s4
	s_add_i32 s18, s5, 1
	s_cmp_ge_u32 s4, s41
	s_cselect_b32 s4, s18, s5
	s_xor_b32 s18, s4, s17
	v_mov_b32_e32 v97, v132
	s_sub_i32 s4, s18, s17
	s_mul_i32 s0, s0, s41
	v_ashrrev_i32_e32 v6, 3, v97
	s_mul_i32 s5, s4, s41
	s_waitcnt vmcnt(8)
	v_ashrrev_i32_e32 v109, 7, v97
	v_bfe_u32 v1, v97, 6, 2
	v_xor_b32_e32 v2, v6, v97
	s_add_i32 s0, s0, s54
	s_sub_i32 s1, s1, s5
	v_and_b32_e32 v108, 31, v97
	v_bitop3_b32 v2, v2, v1, 7 bitop3:0x6c
	v_mul_lo_u32 v1, v109, s6
	s_add_i32 s1, s0, s1
	s_lshl_b32 s0, s4, 7
	v_and_b32_e32 v0, 7, v97
	v_or_b32_e32 v7, v1, v108
	v_lshrrev_b32_e32 v1, 3, v97
	v_readlane_b32 s4, v221, 5
	s_mul_i32 s41, s1, 0xc0
	v_bfe_u32 v115, v97, 5, 1
	v_bitop3_b32 v0, v1, v0, 3 bitop3:0x6c
	v_readlane_b32 s5, v221, 6
	v_xor_b32_e32 v8, v0, v115
	v_add_u32_e32 v3, s41, v6
	v_mov_b64_e32 v[0:1], s[4:5]
	s_movk_i32 s19, 0x1600
	v_mad_i64_i32 v[0:1], s[4:5], v3, s19, v[0:1]
	v_readlane_b32 s4, v220, 56
	v_readlane_b32 s5, v220, 57
	v_lshlrev_b32_e32 v98, 4, v2
	v_add_u32_e32 v9, s0, v6
	v_mov_b64_e32 v[2:3], s[4:5]
	v_lshlrev_b32_e32 v120, 4, v97
	v_mad_i64_i32 v[2:3], s[4:5], v9, s19, v[2:3]
	v_add_u32_e32 v121, 0, v120
	v_mov_b32_e32 v99, v96
	v_readfirstlane_b32 s4, v121
	v_add_u32_e32 v122, 0x1000, v121
	v_lshl_add_u64 v[0:1], v[0:1], 0, v[98:99]
	s_mov_b32 m0, s4
	s_mov_b64 s[42:43], 0x2c000
	v_readfirstlane_b32 s4, v122
	v_add_u32_e32 v123, 0x2000, v121
	global_load_lds_dwordx4 v[0:1], off
	v_lshl_add_u64 v[4:5], v[0:1], 0, s[42:43]
	s_mov_b32 m0, s4
	s_mov_b64 s[44:45], 0x58000
	v_readfirstlane_b32 s4, v123
	v_add_u32_e32 v124, 0x3000, v121
	global_load_lds_dwordx4 v[4:5], off
	v_lshl_add_u64 v[4:5], v[0:1], 0, s[44:45]
	s_mov_b32 m0, s4
	s_mov_b64 s[46:47], 0x84000
	v_readfirstlane_b32 s4, v124
	global_load_lds_dwordx4 v[4:5], off
	v_lshl_add_u64 v[4:5], v[0:1], 0, s[46:47]
	s_mov_b32 m0, s4
	s_mov_b64 s[4:5], 0xb0000
	v_add_u32_e32 v125, 0x4000, v121
	global_load_lds_dwordx4 v[4:5], off
	v_lshl_add_u64 v[4:5], v[0:1], 0, s[4:5]
	v_readfirstlane_b32 s4, v125
	s_mov_b32 m0, s4
	s_mov_b64 s[4:5], 0xdc000
	v_add_u32_e32 v126, 0x5000, v121
	v_lshl_add_u64 v[0:1], v[0:1], 0, s[4:5]
	v_readfirstlane_b32 s4, v126
	v_add_u32_e32 v127, 0xc000, v121
	global_load_lds_dwordx4 v[4:5], off
	s_mov_b32 m0, s4
	v_readfirstlane_b32 s4, v127
	v_add_u32_e32 v128, 0xd000, v121
	global_load_lds_dwordx4 v[0:1], off
	v_lshl_add_u64 v[0:1], v[2:3], 0, v[98:99]
	s_mov_b32 m0, s4
	v_readfirstlane_b32 s4, v128
	v_add_u32_e32 v129, 0xe000, v121
	global_load_lds_dwordx4 v[0:1], off
	v_lshl_add_u64 v[2:3], v[0:1], 0, s[42:43]
	s_mov_b32 m0, s4
	v_readfirstlane_b32 s4, v129
	v_add_u32_e32 v130, 0xf000, v121
	global_load_lds_dwordx4 v[2:3], off
	v_lshl_add_u64 v[2:3], v[0:1], 0, s[44:45]
	s_mov_b32 m0, s4
	v_readfirstlane_b32 s4, v130
	global_load_lds_dwordx4 v[2:3], off
	v_lshl_add_u64 v[0:1], v[0:1], 0, s[46:47]
	s_mov_b32 m0, s4
	s_mul_i32 s15, s15, 7
	global_load_lds_dwordx4 v[0:1], off
	s_add_i32 s17, s17, s15
	s_sub_i32 s4, s17, s18
	s_mul_i32 s16, s16, 7
	s_sub_i32 s4, s4, s16
	v_readlane_b32 s5, v218, 33
	v_lshlrev_b32_e32 v0, 7, v97
	s_mul_i32 s4, s5, s4
	v_and_b32_e32 v0, 0x2f80, v0
	s_add_i32 s4, s4, s39
	s_waitcnt vmcnt(0)
	v_add_u32_e32 v153, 0, v0
	v_add_u32_e32 v155, s10, v0
	v_add_u32_e32 v2, s4, v6
	v_mov_b64_e32 v[0:1], s[70:71]
	v_lshlrev_b32_e32 v154, 4, v8
	v_mad_i64_i32 v[100:101], s[4:5], v2, s19, v[0:1]
	v_mad_i64_i32 v[102:103], s[4:5], v9, s19, v[0:1]
	v_mov_b32_e32 v0, 0
	v_lshl_add_u32 v131, v7, 7, 0
	v_xor_b32_e32 v156, 32, v154
	v_xor_b32_e32 v157, 64, v154
	v_xor_b32_e32 v158, 0x60, v154
	s_mov_b32 s15, 0
	v_mov_b32_e32 v1, v0
	v_mov_b32_e32 v2, v0
	v_mov_b32_e32 v3, v0
	v_mov_b32_e32 v4, v0
	v_mov_b32_e32 v5, v0
	v_mov_b32_e32 v6, v0
	v_mov_b32_e32 v7, v0
	v_mov_b32_e32 v8, v0
	v_mov_b32_e32 v9, v0
	v_mov_b32_e32 v10, v0
	v_mov_b32_e32 v11, v0
	v_mov_b32_e32 v12, v0
	v_mov_b32_e32 v13, v0
	v_mov_b32_e32 v14, v0
	v_mov_b32_e32 v15, v0
	v_mov_b32_e32 v16, v0
	v_mov_b32_e32 v17, v0
	v_mov_b32_e32 v18, v0
	v_mov_b32_e32 v19, v0
	v_mov_b32_e32 v20, v0
	v_mov_b32_e32 v21, v0
	v_mov_b32_e32 v22, v0
	v_mov_b32_e32 v23, v0
	v_mov_b32_e32 v24, v0
	v_mov_b32_e32 v25, v0
	v_mov_b32_e32 v26, v0
	v_mov_b32_e32 v27, v0
	v_mov_b32_e32 v28, v0
	v_mov_b32_e32 v29, v0
	v_mov_b32_e32 v30, v0
	v_mov_b32_e32 v31, v0
	v_mov_b32_e32 v32, v0
	v_mov_b32_e32 v33, v0
	v_mov_b32_e32 v34, v0
	v_mov_b32_e32 v35, v0
	v_mov_b32_e32 v36, v0
	v_mov_b32_e32 v37, v0
	v_mov_b32_e32 v38, v0
	v_mov_b32_e32 v39, v0
	v_mov_b32_e32 v40, v0
	v_mov_b32_e32 v41, v0
	v_mov_b32_e32 v42, v0
	v_mov_b32_e32 v43, v0
	v_mov_b32_e32 v44, v0
	v_mov_b32_e32 v45, v0
	v_mov_b32_e32 v46, v0
	v_mov_b32_e32 v47, v0
	v_mov_b32_e32 v48, v0
	s_waitcnt vmcnt(0)
; template <int EPI, int MI>
; DI void gemm_tile(const GemmDesc& g, int tm, int tn, char* smem) {
;     ...
;   f32x16 acc[MI][2];
; #pragma unroll
;   for (int a = 0; a < MI; ++a)
; #pragma unroll
;     for (int b = 0; b < 2; ++b)
; #pragma unroll
;       for (int i = 0; i < 16; ++i) acc[a][b][i] = 0.f;
;   const int srow = tid >> 3;
;   const int schunk = (tid & 7) ^ ((srow & 7) ^ ((srow >> 3) & 3));
;     ...
;   const int rowA = wm * (32 * MI) + r, rowB = wn * 64 + r;
;   const int hk = hh ^ ((r & 7) ^ ((r >> 3) & 3));
;     ...
;   G_GLDS(0, 0);
;   asm volatile("s_waitcnt vmcnt(0)" ::: "memory");
;   __syncthreads();
;   for (int kt = 0; kt < nk; kt += 2) {
;     if (kt + 1 < nk) G_GLDS(kt + 1, 1);
;     G_COMPUTE(0);
;     asm volatile("s_waitcnt vmcnt(0)" ::: "memory");
;     __syncthreads();
;     if (kt + 1 < nk) {
;       if (kt + 2 < nk) G_GLDS(kt + 2, 0);
;       G_COMPUTE(1);
;       asm volatile("s_waitcnt vmcnt(0)" ::: "memory");
;       __syncthreads();
;     }
;   }
	v_mov_b32_e32 v49, v0
	v_mov_b32_e32 v50, v0
	v_mov_b32_e32 v51, v0
	v_mov_b32_e32 v52, v0
	v_mov_b32_e32 v53, v0
	v_mov_b32_e32 v54, v0
	v_mov_b32_e32 v55, v0
	v_mov_b32_e32 v56, v0
	v_mov_b32_e32 v57, v0
	v_mov_b32_e32 v58, v0
	v_mov_b32_e32 v59, v0
	v_mov_b32_e32 v60, v0
	v_mov_b32_e32 v61, v0
	v_mov_b32_e32 v62, v0
	v_mov_b32_e32 v63, v0
	v_mov_b32_e32 v64, v0
	v_mov_b32_e32 v65, v0
	v_mov_b32_e32 v66, v0
	v_mov_b32_e32 v67, v0
	v_mov_b32_e32 v68, v0
	v_mov_b32_e32 v69, v0
	v_mov_b32_e32 v70, v0
	v_mov_b32_e32 v71, v0
	v_mov_b32_e32 v72, v0
	v_mov_b32_e32 v73, v0
	v_mov_b32_e32 v74, v0
	v_mov_b32_e32 v75, v0
	v_mov_b32_e32 v76, v0
	v_mov_b32_e32 v77, v0
	v_mov_b32_e32 v78, v0
	v_mov_b32_e32 v79, v0
	v_mov_b32_e32 v80, v0
	v_mov_b32_e32 v81, v0
	v_mov_b32_e32 v82, v0
	v_mov_b32_e32 v83, v0
	v_mov_b32_e32 v84, v0
	v_mov_b32_e32 v85, v0
	v_mov_b32_e32 v86, v0
	v_mov_b32_e32 v87, v0
	v_mov_b32_e32 v88, v0
	v_mov_b32_e32 v89, v0
	v_mov_b32_e32 v90, v0
	v_mov_b32_e32 v91, v0
	v_mov_b32_e32 v92, v0
	v_mov_b32_e32 v93, v0
	v_mov_b32_e32 v94, v0
	v_mov_b32_e32 v95, v0
	v_add_u32_e32 v162, v131, v154
	v_add_u32_e32 v163, v131, v156
	v_add_u32_e32 v164, v131, v157
	v_add_u32_e32 v165, v131, v158
	v_add_u32_e32 v166, v153, v154
	v_add_u32_e32 v167, v153, v156
	v_add_u32_e32 v168, v153, v157
	v_add_u32_e32 v169, v153, v158
	v_add_u32_e32 v170, v155, v154
	v_add_u32_e32 v171, v155, v156
	v_add_u32_e32 v172, v155, v157
	v_add_u32_e32 v173, v155, v158
	v_lshl_add_u64 v[252:253], v[100:101], 0, v[98:99]
	v_lshl_add_u64 v[254:255], v[102:103], 0, v[98:99]
	v_readfirstlane_b32 s100, v121
	s_mov_b64 s[4:5], 0x80
	s_waitcnt vmcnt(0) lgkmcnt(0)
	s_barrier
	s_mov_b64 s[16:17], 0x5872080
	s_add_u32 m0, s100, 0x6000
	v_lshl_add_u64 v[106:107], v[252:253], 0, s[16:17]
	global_load_lds_dwordx4 v[106:107], off
	s_mov_b64 s[16:17], 0x589e080
	s_add_u32 m0, s100, 0x7000
	v_lshl_add_u64 v[106:107], v[252:253], 0, s[16:17]
	global_load_lds_dwordx4 v[106:107], off
	ds_read_b128 v[236:239], v166 offset:49152
	ds_read_b128 v[240:243], v166 offset:53248
	ds_read_b128 v[224:227], v162
	ds_read_b128 v[228:231], v162 offset:4096
	s_mov_b32 s15, 0
.Lge_loop:
	ds_read_b128 v[232:235], v162 offset:8192
	s_waitcnt lgkmcnt(2)
	v_mfma_f32_32x32x16_bf16 v[80:95], v[224:227], v[236:239], v[80:95]
	v_mfma_f32_32x32x16_bf16 v[64:79], v[224:227], v[240:243], v[64:79]
	ds_read_b128 v[244:247], v167 offset:49152
	ds_read_b128 v[248:251], v167 offset:53248
	ds_read_b128 v[224:227], v163
	s_waitcnt lgkmcnt(4)
	v_mfma_f32_32x32x16_bf16 v[48:63], v[228:231], v[236:239], v[48:63]
	v_mfma_f32_32x32x16_bf16 v[32:47], v[228:231], v[240:243], v[32:47]
	s_mov_b64 s[16:17], 0x58ca080
	s_add_u32 m0, s100, 0x8000
	v_lshl_add_u64 v[106:107], v[252:253], 0, s[16:17]
	global_load_lds_dwordx4 v[106:107], off
	s_mov_b64 s[16:17], 0x58f6080
	s_add_u32 m0, s100, 0x9000
	v_lshl_add_u64 v[106:107], v[252:253], 0, s[16:17]
	global_load_lds_dwordx4 v[106:107], off
	ds_read_b128 v[228:231], v163 offset:4096
	s_waitcnt lgkmcnt(4)
	v_mfma_f32_32x32x16_bf16 v[16:31], v[232:235], v[236:239], v[16:31]
	v_mfma_f32_32x32x16_bf16 v[0:15], v[232:235], v[240:243], v[0:15]
	s_mov_b64 s[16:17], 0x5922080
	s_add_u32 m0, s100, 0xa000
	v_lshl_add_u64 v[106:107], v[252:253], 0, s[16:17]
	global_load_lds_dwordx4 v[106:107], off
	s_mov_b64 s[16:17], 0x594e080
	s_add_u32 m0, s100, 0xb000
	v_lshl_add_u64 v[106:107], v[252:253], 0, s[16:17]
	global_load_lds_dwordx4 v[106:107], off
	v_lshl_add_u64 v[252:253], v[252:253], 0, s[4:5]
	ds_read_b128 v[232:235], v163 offset:8192
	s_waitcnt lgkmcnt(2)
	v_mfma_f32_32x32x16_bf16 v[80:95], v[224:227], v[244:247], v[80:95]
	v_mfma_f32_32x32x16_bf16 v[64:79], v[224:227], v[248:251], v[64:79]
	s_mov_b64 s[16:17], 0x1b80080
	s_add_u32 m0, s100, 0x10000
	v_lshl_add_u64 v[106:107], v[254:255], 0, s[16:17]
	global_load_lds_dwordx4 v[106:107], off
	s_mov_b64 s[16:17], 0x1bac080
	s_add_u32 m0, s100, 0x11000
	v_lshl_add_u64 v[106:107], v[254:255], 0, s[16:17]
	global_load_lds_dwordx4 v[106:107], off
	ds_read_b128 v[236:239], v168 offset:49152
	ds_read_b128 v[240:243], v168 offset:53248
	ds_read_b128 v[224:227], v164
	s_waitcnt lgkmcnt(4)
	v_mfma_f32_32x32x16_bf16 v[48:63], v[228:231], v[244:247], v[48:63]
	v_mfma_f32_32x32x16_bf16 v[32:47], v[228:231], v[248:251], v[32:47]
	s_mov_b64 s[16:17], 0x1bd8080
	s_add_u32 m0, s100, 0x12000
	v_lshl_add_u64 v[106:107], v[254:255], 0, s[16:17]
	global_load_lds_dwordx4 v[106:107], off
	s_mov_b64 s[16:17], 0x1c04080
	s_add_u32 m0, s100, 0x13000
	v_lshl_add_u64 v[106:107], v[254:255], 0, s[16:17]
	global_load_lds_dwordx4 v[106:107], off
	v_lshl_add_u64 v[254:255], v[254:255], 0, s[4:5]
	ds_read_b128 v[228:231], v164 offset:4096
	s_waitcnt lgkmcnt(4)
	v_mfma_f32_32x32x16_bf16 v[16:31], v[232:235], v[244:247], v[16:31]
	v_mfma_f32_32x32x16_bf16 v[0:15], v[232:235], v[248:251], v[0:15]
	ds_read_b128 v[232:235], v164 offset:8192
	s_waitcnt lgkmcnt(2)
	v_mfma_f32_32x32x16_bf16 v[80:95], v[224:227], v[236:239], v[80:95]
	v_mfma_f32_32x32x16_bf16 v[64:79], v[224:227], v[240:243], v[64:79]
	ds_read_b128 v[244:247], v169 offset:49152
	ds_read_b128 v[248:251], v169 offset:53248
	ds_read_b128 v[224:227], v165
	s_waitcnt lgkmcnt(4)
	v_mfma_f32_32x32x16_bf16 v[48:63], v[228:231], v[236:239], v[48:63]
	v_mfma_f32_32x32x16_bf16 v[32:47], v[228:231], v[240:243], v[32:47]
	ds_read_b128 v[228:231], v165 offset:4096
	s_waitcnt lgkmcnt(4)
	v_mfma_f32_32x32x16_bf16 v[16:31], v[232:235], v[236:239], v[16:31]
	v_mfma_f32_32x32x16_bf16 v[0:15], v[232:235], v[240:243], v[0:15]
	ds_read_b128 v[232:235], v165 offset:8192
	s_waitcnt lgkmcnt(2)
	v_mfma_f32_32x32x16_bf16 v[80:95], v[224:227], v[244:247], v[80:95]
	v_mfma_f32_32x32x16_bf16 v[64:79], v[224:227], v[248:251], v[64:79]
	s_waitcnt lgkmcnt(0)
	s_waitcnt vmcnt(0)
	s_barrier
	s_cmp_eq_u32 s15, 42
	s_cbranch_scc1 .Lge_noearly
	s_mov_b64 s[16:17], 0x5872080
	s_mov_b32 m0, s100
	v_lshl_add_u64 v[106:107], v[252:253], 0, s[16:17]
	global_load_lds_dwordx4 v[106:107], off
	s_mov_b64 s[16:17], 0x589e080
	s_add_u32 m0, s100, 0x1000
	v_lshl_add_u64 v[106:107], v[252:253], 0, s[16:17]
	global_load_lds_dwordx4 v[106:107], off
; template <int EPI, int MI>
; DI void gemm_tile(const GemmDesc& g, int tm, int tn, char* smem) {
;     ...
;   const int rowA = wm * (32 * MI) + r, rowB = wn * 64 + r;
;   const int hk = hh ^ ((r & 7) ^ ((r >> 3) & 3));
;     ...
;   G_GLDS(0, 0);
;   asm volatile("s_waitcnt vmcnt(0)" ::: "memory");
;   __syncthreads();
;   for (int kt = 0; kt < nk; kt += 2) {
;     if (kt + 1 < nk) G_GLDS(kt + 1, 1);
;     G_COMPUTE(0);
;     asm volatile("s_waitcnt vmcnt(0)" ::: "memory");
;     __syncthreads();
;     if (kt + 1 < nk) {
;       if (kt + 2 < nk) G_GLDS(kt + 2, 0);
;       G_COMPUTE(1);
;       asm volatile("s_waitcnt vmcnt(0)" ::: "memory");
;       __syncthreads();
;     }
;   }
.Lge_noearly:
	ds_read_b128 v[236:239], v170
	ds_read_b128 v[240:243], v170 offset:4096
	ds_read_b128 v[224:227], v162 offset:24576
	v_mfma_f32_32x32x16_bf16 v[48:63], v[228:231], v[244:247], v[48:63]
	v_mfma_f32_32x32x16_bf16 v[32:47], v[228:231], v[248:251], v[32:47]
	ds_read_b128 v[228:231], v162 offset:28672
	v_mfma_f32_32x32x16_bf16 v[16:31], v[232:235], v[244:247], v[16:31]
	v_mfma_f32_32x32x16_bf16 v[0:15], v[232:235], v[248:251], v[0:15]
	s_cmp_eq_u32 s15, 42
	s_cbranch_scc1 .Lge_last
	ds_read_b128 v[232:235], v162 offset:32768
	s_waitcnt lgkmcnt(2)
	v_mfma_f32_32x32x16_bf16 v[80:95], v[224:227], v[236:239], v[80:95]
	v_mfma_f32_32x32x16_bf16 v[64:79], v[224:227], v[240:243], v[64:79]
	ds_read_b128 v[244:247], v171
	ds_read_b128 v[248:251], v171 offset:4096
	ds_read_b128 v[224:227], v163 offset:24576
	s_waitcnt lgkmcnt(4)
	v_mfma_f32_32x32x16_bf16 v[48:63], v[228:231], v[236:239], v[48:63]
	v_mfma_f32_32x32x16_bf16 v[32:47], v[228:231], v[240:243], v[32:47]
	s_mov_b64 s[16:17], 0x58ca080
	s_add_u32 m0, s100, 0x2000
	v_lshl_add_u64 v[106:107], v[252:253], 0, s[16:17]
	global_load_lds_dwordx4 v[106:107], off
	s_mov_b64 s[16:17], 0x58f6080
	s_add_u32 m0, s100, 0x3000
	v_lshl_add_u64 v[106:107], v[252:253], 0, s[16:17]
	global_load_lds_dwordx4 v[106:107], off
	ds_read_b128 v[228:231], v163 offset:28672
	s_waitcnt lgkmcnt(4)
	v_mfma_f32_32x32x16_bf16 v[16:31], v[232:235], v[236:239], v[16:31]
	v_mfma_f32_32x32x16_bf16 v[0:15], v[232:235], v[240:243], v[0:15]
	s_mov_b64 s[16:17], 0x5922080
	s_add_u32 m0, s100, 0x4000
	v_lshl_add_u64 v[106:107], v[252:253], 0, s[16:17]
	global_load_lds_dwordx4 v[106:107], off
	s_mov_b64 s[16:17], 0x594e080
	s_add_u32 m0, s100, 0x5000
	v_lshl_add_u64 v[106:107], v[252:253], 0, s[16:17]
	global_load_lds_dwordx4 v[106:107], off
	v_lshl_add_u64 v[252:253], v[252:253], 0, s[4:5]
	ds_read_b128 v[232:235], v163 offset:32768
	s_waitcnt lgkmcnt(2)
	v_mfma_f32_32x32x16_bf16 v[80:95], v[224:227], v[244:247], v[80:95]
	v_mfma_f32_32x32x16_bf16 v[64:79], v[224:227], v[248:251], v[64:79]
	s_mov_b64 s[16:17], 0x1b80080
	s_add_u32 m0, s100, 0xc000
	v_lshl_add_u64 v[106:107], v[254:255], 0, s[16:17]
	global_load_lds_dwordx4 v[106:107], off
	s_mov_b64 s[16:17], 0x1bac080
	s_add_u32 m0, s100, 0xd000
	v_lshl_add_u64 v[106:107], v[254:255], 0, s[16:17]
	global_load_lds_dwordx4 v[106:107], off
	ds_read_b128 v[236:239], v172
	ds_read_b128 v[240:243], v172 offset:4096
	ds_read_b128 v[224:227], v164 offset:24576
	s_waitcnt lgkmcnt(4)
	v_mfma_f32_32x32x16_bf16 v[48:63], v[228:231], v[244:247], v[48:63]
	v_mfma_f32_32x32x16_bf16 v[32:47], v[228:231], v[248:251], v[32:47]
	s_mov_b64 s[16:17], 0x1bd8080
	s_add_u32 m0, s100, 0xe000
	v_lshl_add_u64 v[106:107], v[254:255], 0, s[16:17]
	global_load_lds_dwordx4 v[106:107], off
	s_mov_b64 s[16:17], 0x1c04080
	s_add_u32 m0, s100, 0xf000
	v_lshl_add_u64 v[106:107], v[254:255], 0, s[16:17]
	global_load_lds_dwordx4 v[106:107], off
	v_lshl_add_u64 v[254:255], v[254:255], 0, s[4:5]
	ds_read_b128 v[228:231], v164 offset:28672
	s_waitcnt lgkmcnt(4)
	v_mfma_f32_32x32x16_bf16 v[16:31], v[232:235], v[244:247], v[16:31]
	v_mfma_f32_32x32x16_bf16 v[0:15], v[232:235], v[248:251], v[0:15]
	ds_read_b128 v[232:235], v164 offset:32768
	s_waitcnt lgkmcnt(2)
	v_mfma_f32_32x32x16_bf16 v[80:95], v[224:227], v[236:239], v[80:95]
	v_mfma_f32_32x32x16_bf16 v[64:79], v[224:227], v[240:243], v[64:79]
	ds_read_b128 v[244:247], v173
	ds_read_b128 v[248:251], v173 offset:4096
	ds_read_b128 v[224:227], v165 offset:24576
	s_waitcnt lgkmcnt(4)
	v_mfma_f32_32x32x16_bf16 v[48:63], v[228:231], v[236:239], v[48:63]
	v_mfma_f32_32x32x16_bf16 v[32:47], v[228:231], v[240:243], v[32:47]
	ds_read_b128 v[228:231], v165 offset:28672
	s_waitcnt lgkmcnt(4)
	v_mfma_f32_32x32x16_bf16 v[16:31], v[232:235], v[236:239], v[16:31]
	v_mfma_f32_32x32x16_bf16 v[0:15], v[232:235], v[240:243], v[0:15]
	ds_read_b128 v[232:235], v165 offset:32768
	s_waitcnt lgkmcnt(2)
	v_mfma_f32_32x32x16_bf16 v[80:95], v[224:227], v[244:247], v[80:95]
	v_mfma_f32_32x32x16_bf16 v[64:79], v[224:227], v[248:251], v[64:79]
	s_waitcnt lgkmcnt(0)
	s_waitcnt vmcnt(0)
	s_barrier
	s_mov_b64 s[16:17], 0x5872080
	s_add_u32 m0, s100, 0x6000
	v_lshl_add_u64 v[106:107], v[252:253], 0, s[16:17]
	global_load_lds_dwordx4 v[106:107], off
	s_mov_b64 s[16:17], 0x589e080
	s_add_u32 m0, s100, 0x7000
	v_lshl_add_u64 v[106:107], v[252:253], 0, s[16:17]
	global_load_lds_dwordx4 v[106:107], off
	ds_read_b128 v[236:239], v166 offset:49152
	ds_read_b128 v[240:243], v166 offset:53248
	ds_read_b128 v[224:227], v162
	v_mfma_f32_32x32x16_bf16 v[48:63], v[228:231], v[244:247], v[48:63]
	v_mfma_f32_32x32x16_bf16 v[32:47], v[228:231], v[248:251], v[32:47]
	ds_read_b128 v[228:231], v162 offset:4096
	v_mfma_f32_32x32x16_bf16 v[16:31], v[232:235], v[244:247], v[16:31]
	v_mfma_f32_32x32x16_bf16 v[0:15], v[232:235], v[248:251], v[0:15]
	s_add_u32 s15, s15, 2
	s_branch .Lge_loop
